# full-line epilogue stores in G4/G5/G6: B rows loaded in permuted order so a wave owns 64 contiguous output columns, 64-B halves exchanged with DPP row_ror:8, every store instruction writes 8 full 128-
# speedup vs baseline: 1.0005x; 1.0005x over previous
.LBB0_1085:
	s_cmp_le_i32 s84, s0
	s_cselect_b64 s[2:3], -1, 0
	s_cmp_lt_i32 s0, s85
	s_cselect_b64 s[0:1], -1, 0
	s_and_b64 s[6:7], s[2:3], s[0:1]
	s_andn2_b64 vcc, exec, s[6:7]
	s_cbranch_vccnz .LBB0_1103
	s_mov_b64 s[2:3], s[58:59]
	v_readlane_b32 s0, v254, 2
	s_mov_b32 s1, s57
	v_mov_b32_e32 v1, v0
	v_mov_b32_e32 v4, v0
	s_movk_i32 s12, 0x800
	v_readfirstlane_b32 s18, v4
	s_ashr_i32 s13, s18, 6
	s_cmpk_gt_i32 s1, 0x2ff
	s_cbranch_scc1 .LBB0_1103
	v_bfe_i32 v2, v4, 27, 1
	v_lshlrev_b32_e32 v5, 4, v4
	v_lshrrev_b32_e32 v2, 22, v2
	v_add_u32_e32 v2, v5, v2
	v_and_b32_e32 v2, 0xfffffc00, v2
	v_sub_u32_e32 v2, v5, v2
	v_lshrrev_b32_e32 v6, 4, v2
	v_bitop3_b32 v2, v6, v2, 32 bitop3:0x6c
	v_ashrrev_i32_e32 v7, 31, v2
	v_ashrrev_i32_e32 v1, 31, v4
	v_lshrrev_b32_e32 v7, 26, v7
	v_lshrrev_b32_e32 v1, 26, v1
	v_add_u32_e32 v7, v2, v7
	v_add_u32_e32 v1, v4, v1
	v_ashrrev_i32_e32 v8, 6, v7
	v_and_b32_e32 v7, 0xc0, v7
	v_ashrrev_i32_e32 v1, 6, v1
	v_sub_u32_e32 v2, v2, v7
	v_mov_b32_e32 v10, 1
	v_lshlrev_b32_e32 v6, 3, v1
	v_lshlrev_b32_e32 v1, 5, v1
	v_ashrrev_i16_sdwa v2, v10, sext(v2) dst_sel:DWORD dst_unused:UNUSED_PAD src0_sel:DWORD src1_sel:BYTE_0
	v_and_b32_e32 v6, -16, v6
	v_and_b32_e32 v1, 32, v1
	v_bfe_i32 v2, v2, 0, 16
	v_add_u32_e32 v6, v8, v6
	v_and_b32_e32 v8, 3, v8
	s_mov_b32 s4, 0xfffe0
	v_add_lshl_u32 v2, v1, v2, 1
	v_add_u32_e32 v5, 0x2000, v5
	v_lshlrev_b32_e32 v7, 1, v6
	v_lshrrev_b32_e32 v9, 2, v6
	v_and_or_b32 v8, v6, s4, v8
	v_lshl_add_u32 v1, v6, 12, v2
	v_ashrrev_i32_e32 v6, 31, v5
	v_lshrrev_b32_e32 v6, 22, v6
	v_and_b32_e32 v7, 24, v7
	v_and_b32_e32 v9, 4, v9
	v_add_u32_e32 v6, v5, v6
	v_or3_b32 v7, v8, v9, v7
	v_ashrrev_i32_e32 v6, 10, v6
	v_lshl_add_u32 v2, v7, 12, v2
	v_lshrrev_b32_e32 v251, 8, v0
	v_lshl_add_u32 v2, v251, 17, v2
	v_mul_i32_i24_e32 v7, 0x400, v6
	s_load_dwordx2 s[2:3], s[2:3], 0xe0
	v_sub_u32_e32 v5, v5, v7
	v_lshrrev_b32_e32 v7, 4, v5
	v_bitop3_b32 v5, v7, v5, 32 bitop3:0x6c
	v_ashrrev_i32_e32 v8, 31, v5
	v_lshrrev_b32_e32 v8, 26, v8
	s_waitcnt lgkmcnt(0)
	s_add_u32 s14, s2, 0x9800000
	v_lshlrev_b32_e32 v7, 3, v6
	v_add_u32_e32 v8, v5, v8
	s_addc_u32 s15, s3, 0
	v_and_b32_e32 v7, -16, v7
	v_ashrrev_i32_e32 v9, 6, v8
	s_add_u32 s17, s2, 0x4fc0000
	v_add_u32_e32 v7, v9, v7
	v_and_b32_e32 v9, 3, v9
	s_addc_u32 s33, s3, 0
	s_ashr_i32 s34, s1, 31
	v_and_or_b32 v9, v7, s4, v9
	s_lshl_b32 s4, s13, 10
	s_add_i32 s35, s4, 0
	s_lshr_b32 s4, s34, 29
	s_add_i32 s4, s1, s4
	s_ashr_i32 s5, s4, 3
	s_and_b32 s4, s4, -8
	s_ashr_i32 s19, s18, 8
	s_sub_i32 s4, s1, s4
	s_cmp_lt_i32 s4, 0
	s_movk_i32 s8, 0x61
	s_cselect_b32 s8, s8, 0x60
	s_mul_i32 s4, s4, s8
	s_add_i32 s4, s4, s5
	s_ashr_i32 s5, s4, 31
	s_lshr_b32 s5, s5, 26
	s_add_i32 s5, s4, s5
	s_ashr_i32 s8, s5, 6
	s_and_b32 s5, s5, 0xffc0
	s_sub_i32 s4, s4, s5
	s_bfe_i32 s5, s4, 0x80000
	s_bfe_u32 s5, s5, 0x3000c
	s_add_i32 s5, s4, s5
	s_bfe_i32 s9, s5, 0x80000
	s_and_b32 s5, s5, 0xf8
	s_sub_i32 s4, s4, s5
	s_lshl_b32 s8, s8, 3
	s_sext_i32_i16 s9, s9
	s_sext_i32_i8 s4, s4
	v_and_b32_e32 v8, 0xc0, v8
	s_lshr_b32 s10, s9, 3
	s_add_i32 s22, s8, s4
	v_sub_u32_e32 v5, v5, v8
	s_ashr_i32 s23, s22, 31
	s_bfe_i64 s[4:5], s[10:11], 0x100000
	v_lshlrev_b32_e32 v6, 5, v6
	v_ashrrev_i16_sdwa v5, v10, sext(v5) dst_sel:DWORD dst_unused:UNUSED_PAD src0_sel:DWORD src1_sel:BYTE_0
	v_lshlrev_b32_e32 v8, 1, v7
	v_lshrrev_b32_e32 v10, 2, v7
	s_lshl_b64 s[8:9], s[22:23], 20
	s_lshl_b64 s[4:5], s[4:5], 20
	v_and_b32_e32 v6, 32, v6
	v_bfe_i32 v5, v5, 0, 16
	v_and_b32_e32 v8, 24, v8
	v_and_b32_e32 v10, 4, v10
	s_add_u32 s28, s17, s4
	v_or3_b32 v8, v9, v10, v8
	v_add_lshl_u32 v5, v6, v5, 1
	s_addc_u32 s29, s33, s5
	s_add_i32 s23, s35, 0x10000
	s_mov_b32 m0, s23
	s_nop 0
	global_load_lds_dwordx4 v2, s[28:29]
	v_lshl_add_u32 v133, v8, 12, v5
	v_lshl_add_u32 v133, v251, 17, v133
	v_add_u32_e32 v133, 0x40000, v133
	s_add_i32 s42, s35, 0x12000
	s_mov_b32 m0, s42
	s_nop 0
	global_load_lds_dwordx4 v133, s[28:29]
	s_add_u32 s4, s28, 0x20000
	s_addc_u32 s5, s29, 0
	s_add_i32 s43, s35, 0x14000
	s_mov_b32 m0, s43
	s_nop 0
	global_load_lds_dwordx4 v2, s[4:5]
	s_add_i32 s48, s35, 0x16000
	s_mov_b32 m0, s48
	s_nop 0
	global_load_lds_dwordx4 v133, s[4:5]
	s_add_u32 s30, s14, s8
	s_addc_u32 s31, s15, s9
	s_mov_b32 m0, s35
	s_nop 0
	global_load_lds_dwordx4 v1, s[30:31]
	v_lshl_add_u32 v132, v7, 12, v5
	s_add_i32 s49, s35, 0x2000
	s_mov_b32 m0, s49
	s_nop 0
	global_load_lds_dwordx4 v132, s[30:31]
	s_add_u32 s8, s30, 0x80000
	s_addc_u32 s9, s31, 0
	s_add_i32 s50, s35, 0x4000
	s_mov_b32 m0, s50
	s_nop 0
	global_load_lds_dwordx4 v1, s[8:9]
	s_add_i32 s51, s35, 0x6000
	s_mov_b32 m0, s51
	s_nop 0
	global_load_lds_dwordx4 v132, s[8:9]
	s_cmp_eq_u32 s19, 1
	s_cselect_b64 s[8:9], -1, 0
	s_cmp_lg_u32 s19, 1
	s_cbranch_scc1 .LBB0_1089
	s_barrier
.LBB0_1089:
	s_sext_i32_i8 s64, s10
	s_add_u32 s10, s2, 0x35000000
	s_addc_u32 s11, s3, 0
	s_ashr_i32 s2, s12, 31
	v_lshrrev_b32_e32 v6, 1, v4
	s_lshr_b32 s2, s2, 26
	v_and_b32_e32 v6, 24, v6
	v_and_b32_e32 v5, 15, v4
	s_add_i32 s2, s12, s2
	v_lshlrev_b32_e32 v7, 1, v6
	v_lshlrev_b32_e32 v4, 2, v4
	s_ashr_i32 s53, s2, 6
	v_lshl_or_b32 v134, s19, 6, v5
	v_lshl_or_b32 v5, v5, 6, v7
	s_lshl_b32 s2, s19, 13
	v_and_b32_e32 v4, 32, v4
	v_bitop3_b32 v7, v5, s2, v4 bitop3:0xde
	s_lshl_b32 s2, s13, 5
	s_and_b32 s20, s2, 0x60
	s_ashr_i32 s52, s0, 31
	s_lshl_b32 s2, s20, 7
	v_bitop3_b32 v4, v5, s2, v4 bitop3:0xde
	s_add_u32 s2, s28, 0x80
	s_waitcnt vmcnt(2)
	s_barrier
	s_addc_u32 s3, s29, 0
	s_add_i32 s54, s35, 0x18000
	s_mov_b32 m0, s54
	s_nop 0
	global_load_lds_dwordx4 v2, s[2:3]
	s_add_i32 s55, s35, 0x1a000
	s_mov_b32 m0, s55
	s_nop 0
	global_load_lds_dwordx4 v133, s[2:3]
	s_add_u32 s2, s30, 0x80
	s_addc_u32 s3, s31, 0
	s_add_i32 s56, s35, 0x8000
	s_mov_b32 m0, s56
	s_nop 0
	global_load_lds_dwordx4 v1, s[2:3]
	s_add_i32 s57, s35, 0xa000
	s_mov_b32 m0, s57
	s_nop 0
	global_load_lds_dwordx4 v132, s[2:3]
	s_add_u32 s2, s4, 0x80
	s_addc_u32 s3, s5, 0
	s_add_i32 s58, s35, 0x1c000
	s_mov_b32 m0, s58
	s_nop 0
	global_load_lds_dwordx4 v2, s[2:3]
	s_add_i32 s59, s35, 0x1e000
	s_mov_b32 m0, s59
	s_nop 0
	global_load_lds_dwordx4 v133, s[2:3]
	s_cmp_gt_i32 s12, 63
	s_waitcnt vmcnt(6)
	s_cselect_b64 s[12:13], -1, 0
	s_add_i32 s60, s53, -2
	s_add_i32 s61, s35, 0xc000
	s_cmpk_lt_u32 s18, 0x100
	s_cselect_b64 s[18:19], -1, 0
	s_add_i32 s62, s35, 0xe000
	v_or_b32_e32 v135, s20, v6
	s_mov_b32 s63, 0
	v_add_u32_e32 v136, 0, v4
	v_add_u32_e32 v137, 0, v7
	s_barrier
	v_and_b32_e32 v253, 0x47, v134
	v_lshlrev_b32_e32 v253, 12, v253
	v_and_b32_e32 v252, 0x60, v135
	v_lshl_add_u32 v253, v252, 2, v253
	v_bfe_u32 v252, v135, 3, 2
	v_lshl_add_u32 v253, v252, 4, v253
	v_bfe_u32 v252, v134, 3, 1
	v_lshl_add_u32 v253, v252, 6, v253
	s_branch .LBB0_1092

.LBB0_1096:
	v_add_u32_e32 v150, 0x10000, v136
	v_add_u32_e32 v166, 0x14000, v136
	ds_read_b128 v[138:141], v150
	ds_read_b128 v[142:145], v150 offset:1024
	ds_read_b128 v[146:149], v150 offset:2048
	ds_read_b128 v[150:153], v150 offset:3072
	ds_read_b128 v[154:157], v166
	ds_read_b128 v[158:161], v166 offset:1024
	ds_read_b128 v[162:165], v166 offset:2048
	ds_read_b128 v[166:169], v166 offset:3072
	s_add_i32 s71, s30, 2
	s_cmp_eq_u32 s60, s30
	s_cselect_b32 s40, s21, s67
	s_cselect_b32 s41, s3, s68
	s_cselect_b32 s38, s66, s69
	s_cselect_b32 s39, s65, s70
	s_add_u32 s30, s40, 0x80
	s_addc_u32 s31, s41, 0
	ds_read_b128 v[170:173], v137
	ds_read_b128 v[174:177], v137 offset:1024
	ds_read_b128 v[178:181], v137 offset:2048
	ds_read_b128 v[182:185], v137 offset:3072
	ds_read_b128 v[186:189], v137 offset:4096
	ds_read_b128 v[190:193], v137 offset:5120
	ds_read_b128 v[194:197], v137 offset:6144
	ds_read_b128 v[202:205], v137 offset:7168
	s_mov_b32 m0, s61
	s_nop 0
	global_load_lds_dwordx4 v1, s[28:29]
	s_mov_b32 m0, s62
	s_nop 0
	global_load_lds_dwordx4 v132, s[28:29]
	s_waitcnt vmcnt(8)
	s_waitcnt lgkmcnt(0)
	s_barrier
	s_setprio 1
	s_waitcnt lgkmcnt(7)
	v_mfma_f32_16x16x32_bf16 v[124:127], v[138:141], v[170:173], v[124:127]
	v_mfma_f32_16x16x32_bf16 v[128:131], v[146:149], v[170:173], v[128:131]
	s_waitcnt lgkmcnt(5)
	v_mfma_f32_16x16x32_bf16 v[112:115], v[138:141], v[178:181], v[112:115]
	v_mfma_f32_16x16x32_bf16 v[108:111], v[146:149], v[178:181], v[108:111]
	s_waitcnt lgkmcnt(3)
	v_mfma_f32_16x16x32_bf16 v[96:99], v[138:141], v[186:189], v[96:99]
	v_mfma_f32_16x16x32_bf16 v[92:95], v[146:149], v[186:189], v[92:95]
	s_waitcnt lgkmcnt(1)
	v_mfma_f32_16x16x32_bf16 v[80:83], v[138:141], v[194:197], v[80:83]
	v_mfma_f32_16x16x32_bf16 v[76:79], v[146:149], v[194:197], v[76:79]
	v_mfma_f32_16x16x32_bf16 v[124:127], v[142:145], v[174:177], v[124:127]
	v_mfma_f32_16x16x32_bf16 v[128:131], v[150:153], v[174:177], v[128:131]
	v_mfma_f32_16x16x32_bf16 v[112:115], v[142:145], v[182:185], v[112:115]
	v_mfma_f32_16x16x32_bf16 v[108:111], v[150:153], v[182:185], v[108:111]
	v_mfma_f32_16x16x32_bf16 v[96:99], v[142:145], v[190:193], v[96:99]
	v_mfma_f32_16x16x32_bf16 v[92:95], v[150:153], v[190:193], v[92:95]
	s_waitcnt lgkmcnt(0)
	v_mfma_f32_16x16x32_bf16 v[80:83], v[142:145], v[202:205], v[80:83]
	v_mfma_f32_16x16x32_bf16 v[76:79], v[150:153], v[202:205], v[76:79]
	s_setprio 0
	s_setprio 1
	v_mfma_f32_16x16x32_bf16 v[120:123], v[154:157], v[170:173], v[120:123]
	v_mfma_f32_16x16x32_bf16 v[116:119], v[162:165], v[170:173], v[116:119]
	v_mfma_f32_16x16x32_bf16 v[104:107], v[154:157], v[178:181], v[104:107]
	v_mfma_f32_16x16x32_bf16 v[100:103], v[162:165], v[178:181], v[100:103]
	v_mfma_f32_16x16x32_bf16 v[88:91], v[154:157], v[186:189], v[88:91]
	v_mfma_f32_16x16x32_bf16 v[84:87], v[162:165], v[186:189], v[84:87]
	v_mfma_f32_16x16x32_bf16 v[72:75], v[154:157], v[194:197], v[72:75]
	v_mfma_f32_16x16x32_bf16 v[68:71], v[162:165], v[194:197], v[68:71]
	v_mfma_f32_16x16x32_bf16 v[120:123], v[158:161], v[174:177], v[120:123]
	v_mfma_f32_16x16x32_bf16 v[116:119], v[166:169], v[174:177], v[116:119]
	v_mfma_f32_16x16x32_bf16 v[104:107], v[158:161], v[182:185], v[104:107]
	v_mfma_f32_16x16x32_bf16 v[100:103], v[166:169], v[182:185], v[100:103]
	v_mfma_f32_16x16x32_bf16 v[88:91], v[158:161], v[190:193], v[88:91]
	v_mfma_f32_16x16x32_bf16 v[84:87], v[166:169], v[190:193], v[84:87]
	v_mfma_f32_16x16x32_bf16 v[72:75], v[158:161], v[202:205], v[72:75]
	v_mfma_f32_16x16x32_bf16 v[68:71], v[166:169], v[202:205], v[68:71]
	s_setprio 0
	s_barrier
	ds_read_b128 v[170:173], v137 offset:16384
	ds_read_b128 v[174:177], v137 offset:17408
	ds_read_b128 v[178:181], v137 offset:18432
	ds_read_b128 v[182:185], v137 offset:19456
	ds_read_b128 v[186:189], v137 offset:20480
	ds_read_b128 v[190:193], v137 offset:21504
	ds_read_b128 v[194:197], v137 offset:22528
	ds_read_b128 v[202:205], v137 offset:23552
	s_mov_b32 m0, s23
	s_nop 0
	global_load_lds_dwordx4 v2, s[38:39]
	s_mov_b32 m0, s42
	s_nop 0
	global_load_lds_dwordx4 v133, s[38:39]
	s_add_u32 s72, s38, 0x20000
	s_addc_u32 s73, s39, 0
	s_mov_b32 m0, s43
	s_nop 0
	global_load_lds_dwordx4 v2, s[72:73]
	s_mov_b32 m0, s48
	s_nop 0
	global_load_lds_dwordx4 v133, s[72:73]
	s_mov_b32 m0, s35
	s_nop 0
	global_load_lds_dwordx4 v1, s[40:41]
	s_mov_b32 m0, s49
	s_nop 0
	global_load_lds_dwordx4 v132, s[40:41]
	s_waitcnt vmcnt(8)
	s_waitcnt lgkmcnt(0)
	s_barrier
	s_setprio 1
	s_waitcnt lgkmcnt(7)
	v_mfma_f32_16x16x32_bf16 v[64:67], v[138:141], v[170:173], v[64:67]
	v_mfma_f32_16x16x32_bf16 v[60:63], v[146:149], v[170:173], v[60:63]
	s_waitcnt lgkmcnt(5)
	v_mfma_f32_16x16x32_bf16 v[48:51], v[138:141], v[178:181], v[48:51]
	v_mfma_f32_16x16x32_bf16 v[44:47], v[146:149], v[178:181], v[44:47]
	s_waitcnt lgkmcnt(3)
	v_mfma_f32_16x16x32_bf16 v[32:35], v[138:141], v[186:189], v[32:35]
	v_mfma_f32_16x16x32_bf16 v[28:31], v[146:149], v[186:189], v[28:31]
	s_waitcnt lgkmcnt(1)
	v_mfma_f32_16x16x32_bf16 v[16:19], v[138:141], v[194:197], v[16:19]
	v_mfma_f32_16x16x32_bf16 v[12:15], v[146:149], v[194:197], v[12:15]
	v_mfma_f32_16x16x32_bf16 v[64:67], v[142:145], v[174:177], v[64:67]
	v_mfma_f32_16x16x32_bf16 v[60:63], v[150:153], v[174:177], v[60:63]
	v_mfma_f32_16x16x32_bf16 v[48:51], v[142:145], v[182:185], v[48:51]
	v_mfma_f32_16x16x32_bf16 v[44:47], v[150:153], v[182:185], v[44:47]
	v_mfma_f32_16x16x32_bf16 v[32:35], v[142:145], v[190:193], v[32:35]
	v_mfma_f32_16x16x32_bf16 v[28:31], v[150:153], v[190:193], v[28:31]
	s_waitcnt lgkmcnt(0)
	v_mfma_f32_16x16x32_bf16 v[16:19], v[142:145], v[202:205], v[16:19]
	v_mfma_f32_16x16x32_bf16 v[12:15], v[150:153], v[202:205], v[12:15]
	s_setprio 0
	s_setprio 1
	v_mfma_f32_16x16x32_bf16 v[56:59], v[154:157], v[170:173], v[56:59]
	v_mfma_f32_16x16x32_bf16 v[52:55], v[162:165], v[170:173], v[52:55]
	v_mfma_f32_16x16x32_bf16 v[40:43], v[154:157], v[178:181], v[40:43]
	v_mfma_f32_16x16x32_bf16 v[36:39], v[162:165], v[178:181], v[36:39]
	v_mfma_f32_16x16x32_bf16 v[24:27], v[154:157], v[186:189], v[24:27]
	v_mfma_f32_16x16x32_bf16 v[20:23], v[162:165], v[186:189], v[20:23]
	v_mfma_f32_16x16x32_bf16 v[8:11], v[154:157], v[194:197], v[8:11]
	v_mfma_f32_16x16x32_bf16 v[4:7], v[162:165], v[194:197], v[4:7]
	v_mfma_f32_16x16x32_bf16 v[56:59], v[158:161], v[174:177], v[56:59]
	v_mfma_f32_16x16x32_bf16 v[52:55], v[166:169], v[174:177], v[52:55]
	v_mfma_f32_16x16x32_bf16 v[40:43], v[158:161], v[182:185], v[40:43]
	v_mfma_f32_16x16x32_bf16 v[36:39], v[166:169], v[182:185], v[36:39]
	v_mfma_f32_16x16x32_bf16 v[24:27], v[158:161], v[190:193], v[24:27]
	v_mfma_f32_16x16x32_bf16 v[20:23], v[166:169], v[190:193], v[20:23]
	v_mfma_f32_16x16x32_bf16 v[8:11], v[158:161], v[202:205], v[8:11]
	v_mfma_f32_16x16x32_bf16 v[4:7], v[166:169], v[202:205], v[4:7]
	s_setprio 0
	s_barrier
	v_add_u32_e32 v150, 0x18000, v136
	v_add_u32_e32 v166, 0x1c000, v136
	ds_read_b128 v[138:141], v150
	ds_read_b128 v[142:145], v150 offset:1024
	ds_read_b128 v[146:149], v150 offset:2048
	ds_read_b128 v[150:153], v150 offset:3072
	ds_read_b128 v[154:157], v166
	ds_read_b128 v[158:161], v166 offset:1024
	ds_read_b128 v[162:165], v166 offset:2048
	ds_read_b128 v[166:169], v166 offset:3072
	ds_read_b128 v[170:173], v137 offset:32768
	ds_read_b128 v[174:177], v137 offset:33792
	ds_read_b128 v[178:181], v137 offset:34816
	ds_read_b128 v[182:185], v137 offset:35840
	ds_read_b128 v[186:189], v137 offset:36864
	ds_read_b128 v[190:193], v137 offset:37888
	ds_read_b128 v[194:197], v137 offset:38912
	ds_read_b128 v[202:205], v137 offset:39936
	s_add_u32 s40, s40, 0x80000
	s_addc_u32 s41, s41, 0
	s_mov_b32 m0, s50
	s_nop 0
	global_load_lds_dwordx4 v1, s[40:41]
	s_mov_b32 m0, s51
	s_nop 0
	global_load_lds_dwordx4 v132, s[40:41]
	s_waitcnt vmcnt(8)
	s_waitcnt lgkmcnt(0)
	s_barrier
	s_setprio 1
	s_waitcnt lgkmcnt(7)
	v_mfma_f32_16x16x32_bf16 v[124:127], v[138:141], v[170:173], v[124:127]
	v_mfma_f32_16x16x32_bf16 v[128:131], v[146:149], v[170:173], v[128:131]
	s_waitcnt lgkmcnt(5)
	v_mfma_f32_16x16x32_bf16 v[112:115], v[138:141], v[178:181], v[112:115]
	v_mfma_f32_16x16x32_bf16 v[108:111], v[146:149], v[178:181], v[108:111]
	s_waitcnt lgkmcnt(3)
	v_mfma_f32_16x16x32_bf16 v[96:99], v[138:141], v[186:189], v[96:99]
	v_mfma_f32_16x16x32_bf16 v[92:95], v[146:149], v[186:189], v[92:95]
	s_waitcnt lgkmcnt(1)
	v_mfma_f32_16x16x32_bf16 v[80:83], v[138:141], v[194:197], v[80:83]
	v_mfma_f32_16x16x32_bf16 v[76:79], v[146:149], v[194:197], v[76:79]
	v_mfma_f32_16x16x32_bf16 v[124:127], v[142:145], v[174:177], v[124:127]
	v_mfma_f32_16x16x32_bf16 v[128:131], v[150:153], v[174:177], v[128:131]
	v_mfma_f32_16x16x32_bf16 v[112:115], v[142:145], v[182:185], v[112:115]
	v_mfma_f32_16x16x32_bf16 v[108:111], v[150:153], v[182:185], v[108:111]
	v_mfma_f32_16x16x32_bf16 v[96:99], v[142:145], v[190:193], v[96:99]
	v_mfma_f32_16x16x32_bf16 v[92:95], v[150:153], v[190:193], v[92:95]
	s_waitcnt lgkmcnt(0)
	v_mfma_f32_16x16x32_bf16 v[80:83], v[142:145], v[202:205], v[80:83]
	v_mfma_f32_16x16x32_bf16 v[76:79], v[150:153], v[202:205], v[76:79]
	s_setprio 0
	s_setprio 1
	v_mfma_f32_16x16x32_bf16 v[120:123], v[154:157], v[170:173], v[120:123]
	v_mfma_f32_16x16x32_bf16 v[116:119], v[162:165], v[170:173], v[116:119]
	v_mfma_f32_16x16x32_bf16 v[104:107], v[154:157], v[178:181], v[104:107]
	v_mfma_f32_16x16x32_bf16 v[100:103], v[162:165], v[178:181], v[100:103]
	v_mfma_f32_16x16x32_bf16 v[88:91], v[154:157], v[186:189], v[88:91]
	v_mfma_f32_16x16x32_bf16 v[84:87], v[162:165], v[186:189], v[84:87]
	v_mfma_f32_16x16x32_bf16 v[72:75], v[154:157], v[194:197], v[72:75]
	v_mfma_f32_16x16x32_bf16 v[68:71], v[162:165], v[194:197], v[68:71]
	v_mfma_f32_16x16x32_bf16 v[120:123], v[158:161], v[174:177], v[120:123]
	v_mfma_f32_16x16x32_bf16 v[116:119], v[166:169], v[174:177], v[116:119]
	v_mfma_f32_16x16x32_bf16 v[104:107], v[158:161], v[182:185], v[104:107]
	v_mfma_f32_16x16x32_bf16 v[100:103], v[166:169], v[182:185], v[100:103]
	v_mfma_f32_16x16x32_bf16 v[88:91], v[158:161], v[190:193], v[88:91]
	v_mfma_f32_16x16x32_bf16 v[84:87], v[166:169], v[190:193], v[84:87]
	v_mfma_f32_16x16x32_bf16 v[72:75], v[158:161], v[202:205], v[72:75]
	v_mfma_f32_16x16x32_bf16 v[68:71], v[166:169], v[202:205], v[68:71]
	s_setprio 0
	s_barrier
	ds_read_b128 v[170:173], v137 offset:49152
	ds_read_b128 v[174:177], v137 offset:50176
	ds_read_b128 v[178:181], v137 offset:51200
	ds_read_b128 v[182:185], v137 offset:52224
	ds_read_b128 v[186:189], v137 offset:53248
	ds_read_b128 v[190:193], v137 offset:54272
	ds_read_b128 v[194:197], v137 offset:55296
	ds_read_b128 v[202:205], v137 offset:56320
	s_add_u32 s40, s38, 0x80
	s_addc_u32 s41, s39, 0
	s_mov_b32 m0, s54
	s_nop 0
	global_load_lds_dwordx4 v2, s[40:41]
	s_add_u32 s38, s38, 0x20080
	s_mov_b32 m0, s55
	s_nop 0
	global_load_lds_dwordx4 v133, s[40:41]
	s_addc_u32 s39, s39, 0
	s_mov_b32 m0, s58
	s_nop 0
	global_load_lds_dwordx4 v2, s[38:39]
	s_mov_b32 m0, s59
	s_nop 0
	global_load_lds_dwordx4 v133, s[38:39]
	s_mov_b32 m0, s56
	s_nop 0
	global_load_lds_dwordx4 v1, s[30:31]
	s_mov_b32 m0, s57
	s_nop 0
	global_load_lds_dwordx4 v132, s[30:31]
	s_waitcnt vmcnt(8)
	s_waitcnt lgkmcnt(0)
	s_barrier
	s_setprio 1
	s_waitcnt lgkmcnt(7)
	v_mfma_f32_16x16x32_bf16 v[64:67], v[138:141], v[170:173], v[64:67]
	v_mfma_f32_16x16x32_bf16 v[60:63], v[146:149], v[170:173], v[60:63]
	s_waitcnt lgkmcnt(5)
	v_mfma_f32_16x16x32_bf16 v[48:51], v[138:141], v[178:181], v[48:51]
	v_mfma_f32_16x16x32_bf16 v[44:47], v[146:149], v[178:181], v[44:47]
	s_waitcnt lgkmcnt(3)
	v_mfma_f32_16x16x32_bf16 v[32:35], v[138:141], v[186:189], v[32:35]
	v_mfma_f32_16x16x32_bf16 v[28:31], v[146:149], v[186:189], v[28:31]
	s_waitcnt lgkmcnt(1)
	v_mfma_f32_16x16x32_bf16 v[16:19], v[138:141], v[194:197], v[16:19]
	v_mfma_f32_16x16x32_bf16 v[12:15], v[146:149], v[194:197], v[12:15]
	v_mfma_f32_16x16x32_bf16 v[64:67], v[142:145], v[174:177], v[64:67]
	v_mfma_f32_16x16x32_bf16 v[60:63], v[150:153], v[174:177], v[60:63]
	v_mfma_f32_16x16x32_bf16 v[48:51], v[142:145], v[182:185], v[48:51]
	v_mfma_f32_16x16x32_bf16 v[44:47], v[150:153], v[182:185], v[44:47]
	v_mfma_f32_16x16x32_bf16 v[32:35], v[142:145], v[190:193], v[32:35]
	v_mfma_f32_16x16x32_bf16 v[28:31], v[150:153], v[190:193], v[28:31]
	s_waitcnt lgkmcnt(0)
	v_mfma_f32_16x16x32_bf16 v[16:19], v[142:145], v[202:205], v[16:19]
	v_mfma_f32_16x16x32_bf16 v[12:15], v[150:153], v[202:205], v[12:15]
	s_setprio 0
	s_setprio 1
	v_mfma_f32_16x16x32_bf16 v[56:59], v[154:157], v[170:173], v[56:59]
	v_mfma_f32_16x16x32_bf16 v[52:55], v[162:165], v[170:173], v[52:55]
	v_mfma_f32_16x16x32_bf16 v[40:43], v[154:157], v[178:181], v[40:43]
	v_mfma_f32_16x16x32_bf16 v[36:39], v[162:165], v[178:181], v[36:39]
	v_mfma_f32_16x16x32_bf16 v[24:27], v[154:157], v[186:189], v[24:27]
	v_mfma_f32_16x16x32_bf16 v[20:23], v[162:165], v[186:189], v[20:23]
	v_mfma_f32_16x16x32_bf16 v[8:11], v[154:157], v[194:197], v[8:11]
	v_mfma_f32_16x16x32_bf16 v[4:7], v[162:165], v[194:197], v[4:7]
	v_mfma_f32_16x16x32_bf16 v[56:59], v[158:161], v[174:177], v[56:59]
	v_mfma_f32_16x16x32_bf16 v[52:55], v[166:169], v[174:177], v[52:55]
	v_mfma_f32_16x16x32_bf16 v[40:43], v[158:161], v[182:185], v[40:43]
	v_mfma_f32_16x16x32_bf16 v[36:39], v[166:169], v[182:185], v[36:39]
	v_mfma_f32_16x16x32_bf16 v[24:27], v[158:161], v[190:193], v[24:27]
	v_mfma_f32_16x16x32_bf16 v[20:23], v[166:169], v[190:193], v[20:23]
	v_mfma_f32_16x16x32_bf16 v[8:11], v[158:161], v[202:205], v[8:11]
	v_mfma_f32_16x16x32_bf16 v[4:7], v[166:169], v[202:205], v[4:7]
	s_setprio 0
	s_barrier
	s_add_u32 s67, s67, 0x100
	s_addc_u32 s68, s68, 0
	s_add_u32 s69, s69, 0x100
	s_addc_u32 s70, s70, 0
	s_add_u32 s28, s28, 0x100
	s_addc_u32 s29, s29, 0
	s_cmp_ge_i32 s71, s53
	s_mov_b32 s30, s71
	s_cbranch_scc0 .LBB0_1096

.LBB0_1099:
	s_nop 15
	s_nop 7
	s_lshl_b32 s96, s22, 20
	s_lshl_b32 s97, s64, 9
	s_add_u32 s96, s96, s97
	s_add_u32 s96, s10, s96
	s_addc_u32 s97, s11, 0
	v_cvt_pk_bf16_f32 v222, v124, v125
	v_cvt_pk_bf16_f32 v223, v126, v127
	v_cvt_pk_bf16_f32 v224, v128, v129
	v_cvt_pk_bf16_f32 v225, v130, v131
	v_cvt_pk_bf16_f32 v226, v120, v121
	v_cvt_pk_bf16_f32 v227, v122, v123
	v_cvt_pk_bf16_f32 v228, v116, v117
	v_cvt_pk_bf16_f32 v229, v118, v119
	v_mov_b32_e32 v124, v222
	v_mov_b32_e32 v125, v223
	v_mov_b32_e32 v126, v224
	v_mov_b32_e32 v127, v225
	v_mov_b32_dpp v222, v226 row_ror:8 row_mask:0xf bank_mask:0xc
	v_mov_b32_dpp v223, v227 row_ror:8 row_mask:0xf bank_mask:0xc
	v_mov_b32_dpp v224, v228 row_ror:8 row_mask:0xf bank_mask:0xc
	v_mov_b32_dpp v225, v229 row_ror:8 row_mask:0xf bank_mask:0xc
	v_mov_b32_dpp v226, v124 row_ror:8 row_mask:0xf bank_mask:0x3
	v_mov_b32_dpp v227, v125 row_ror:8 row_mask:0xf bank_mask:0x3
	v_mov_b32_dpp v228, v126 row_ror:8 row_mask:0xf bank_mask:0x3
	v_mov_b32_dpp v229, v127 row_ror:8 row_mask:0xf bank_mask:0x3
	s_add_u32 s88, s96, 0x0
	s_addc_u32 s89, s97, 0
	global_store_dwordx4 v253, v[222:225], s[88:89]
	s_add_u32 s88, s96, 0x8000
	s_addc_u32 s89, s97, 0
	global_store_dwordx4 v253, v[226:229], s[88:89]
	v_cvt_pk_bf16_f32 v230, v112, v113
	v_cvt_pk_bf16_f32 v231, v114, v115
	v_cvt_pk_bf16_f32 v232, v108, v109
	v_cvt_pk_bf16_f32 v233, v110, v111
	v_cvt_pk_bf16_f32 v234, v104, v105
	v_cvt_pk_bf16_f32 v235, v106, v107
	v_cvt_pk_bf16_f32 v236, v100, v101
	v_cvt_pk_bf16_f32 v237, v102, v103
	v_mov_b32_e32 v112, v230
	v_mov_b32_e32 v113, v231
	v_mov_b32_e32 v114, v232
	v_mov_b32_e32 v115, v233
	v_mov_b32_dpp v230, v234 row_ror:8 row_mask:0xf bank_mask:0xc
	v_mov_b32_dpp v231, v235 row_ror:8 row_mask:0xf bank_mask:0xc
	v_mov_b32_dpp v232, v236 row_ror:8 row_mask:0xf bank_mask:0xc
	v_mov_b32_dpp v233, v237 row_ror:8 row_mask:0xf bank_mask:0xc
	v_mov_b32_dpp v234, v112 row_ror:8 row_mask:0xf bank_mask:0x3
	v_mov_b32_dpp v235, v113 row_ror:8 row_mask:0xf bank_mask:0x3
	v_mov_b32_dpp v236, v114 row_ror:8 row_mask:0xf bank_mask:0x3
	v_mov_b32_dpp v237, v115 row_ror:8 row_mask:0xf bank_mask:0x3
	s_add_u32 s88, s96, 0x10000
	s_addc_u32 s89, s97, 0
	global_store_dwordx4 v253, v[230:233], s[88:89]
	s_add_u32 s88, s96, 0x18000
	s_addc_u32 s89, s97, 0
	global_store_dwordx4 v253, v[234:237], s[88:89]
	v_cvt_pk_bf16_f32 v238, v96, v97
	v_cvt_pk_bf16_f32 v239, v98, v99
	v_cvt_pk_bf16_f32 v240, v92, v93
	v_cvt_pk_bf16_f32 v241, v94, v95
	v_cvt_pk_bf16_f32 v242, v88, v89
	v_cvt_pk_bf16_f32 v243, v90, v91
	v_cvt_pk_bf16_f32 v244, v84, v85
	v_cvt_pk_bf16_f32 v245, v86, v87
	v_mov_b32_e32 v96, v238
	v_mov_b32_e32 v97, v239
	v_mov_b32_e32 v98, v240
	v_mov_b32_e32 v99, v241
	v_mov_b32_dpp v238, v242 row_ror:8 row_mask:0xf bank_mask:0xc
	v_mov_b32_dpp v239, v243 row_ror:8 row_mask:0xf bank_mask:0xc
	v_mov_b32_dpp v240, v244 row_ror:8 row_mask:0xf bank_mask:0xc
	v_mov_b32_dpp v241, v245 row_ror:8 row_mask:0xf bank_mask:0xc
	v_mov_b32_dpp v242, v96 row_ror:8 row_mask:0xf bank_mask:0x3
	v_mov_b32_dpp v243, v97 row_ror:8 row_mask:0xf bank_mask:0x3
	v_mov_b32_dpp v244, v98 row_ror:8 row_mask:0xf bank_mask:0x3
	v_mov_b32_dpp v245, v99 row_ror:8 row_mask:0xf bank_mask:0x3
	s_add_u32 s88, s96, 0x20000
	s_addc_u32 s89, s97, 0
	global_store_dwordx4 v253, v[238:241], s[88:89]
	s_add_u32 s88, s96, 0x28000
	s_addc_u32 s89, s97, 0
	global_store_dwordx4 v253, v[242:245], s[88:89]
	v_cvt_pk_bf16_f32 v222, v80, v81
	v_cvt_pk_bf16_f32 v223, v82, v83
	v_cvt_pk_bf16_f32 v224, v76, v77
	v_cvt_pk_bf16_f32 v225, v78, v79
	v_cvt_pk_bf16_f32 v226, v72, v73
	v_cvt_pk_bf16_f32 v227, v74, v75
	v_cvt_pk_bf16_f32 v228, v68, v69
	v_cvt_pk_bf16_f32 v229, v70, v71
	v_mov_b32_e32 v80, v222
	v_mov_b32_e32 v81, v223
	v_mov_b32_e32 v82, v224
	v_mov_b32_e32 v83, v225
	v_mov_b32_dpp v222, v226 row_ror:8 row_mask:0xf bank_mask:0xc
	v_mov_b32_dpp v223, v227 row_ror:8 row_mask:0xf bank_mask:0xc
	v_mov_b32_dpp v224, v228 row_ror:8 row_mask:0xf bank_mask:0xc
	v_mov_b32_dpp v225, v229 row_ror:8 row_mask:0xf bank_mask:0xc
	v_mov_b32_dpp v226, v80 row_ror:8 row_mask:0xf bank_mask:0x3
	v_mov_b32_dpp v227, v81 row_ror:8 row_mask:0xf bank_mask:0x3
	v_mov_b32_dpp v228, v82 row_ror:8 row_mask:0xf bank_mask:0x3
	v_mov_b32_dpp v229, v83 row_ror:8 row_mask:0xf bank_mask:0x3
	s_add_u32 s88, s96, 0x30000
	s_addc_u32 s89, s97, 0
	global_store_dwordx4 v253, v[222:225], s[88:89]
	s_add_u32 s88, s96, 0x38000
	s_addc_u32 s89, s97, 0
	global_store_dwordx4 v253, v[226:229], s[88:89]
	v_cvt_pk_bf16_f32 v230, v64, v65
	v_cvt_pk_bf16_f32 v231, v66, v67
	v_cvt_pk_bf16_f32 v232, v60, v61
	v_cvt_pk_bf16_f32 v233, v62, v63
	v_cvt_pk_bf16_f32 v234, v56, v57
	v_cvt_pk_bf16_f32 v235, v58, v59
	v_cvt_pk_bf16_f32 v236, v52, v53
	v_cvt_pk_bf16_f32 v237, v54, v55
	v_mov_b32_e32 v64, v230
	v_mov_b32_e32 v65, v231
	v_mov_b32_e32 v66, v232
	v_mov_b32_e32 v67, v233
	v_mov_b32_dpp v230, v234 row_ror:8 row_mask:0xf bank_mask:0xc
	v_mov_b32_dpp v231, v235 row_ror:8 row_mask:0xf bank_mask:0xc
	v_mov_b32_dpp v232, v236 row_ror:8 row_mask:0xf bank_mask:0xc
	v_mov_b32_dpp v233, v237 row_ror:8 row_mask:0xf bank_mask:0xc
	v_mov_b32_dpp v234, v64 row_ror:8 row_mask:0xf bank_mask:0x3
	v_mov_b32_dpp v235, v65 row_ror:8 row_mask:0xf bank_mask:0x3
	v_mov_b32_dpp v236, v66 row_ror:8 row_mask:0xf bank_mask:0x3
	v_mov_b32_dpp v237, v67 row_ror:8 row_mask:0xf bank_mask:0x3
	s_add_u32 s88, s96, 0x80000
	s_addc_u32 s89, s97, 0
	global_store_dwordx4 v253, v[230:233], s[88:89]
	s_add_u32 s88, s96, 0x88000
	s_addc_u32 s89, s97, 0
	global_store_dwordx4 v253, v[234:237], s[88:89]
	v_cvt_pk_bf16_f32 v238, v48, v49
	v_cvt_pk_bf16_f32 v239, v50, v51
	v_cvt_pk_bf16_f32 v240, v44, v45
	v_cvt_pk_bf16_f32 v241, v46, v47
	v_cvt_pk_bf16_f32 v242, v40, v41
	v_cvt_pk_bf16_f32 v243, v42, v43
	v_cvt_pk_bf16_f32 v244, v36, v37
	v_cvt_pk_bf16_f32 v245, v38, v39
	v_mov_b32_e32 v48, v238
	v_mov_b32_e32 v49, v239
	v_mov_b32_e32 v50, v240
	v_mov_b32_e32 v51, v241
	v_mov_b32_dpp v238, v242 row_ror:8 row_mask:0xf bank_mask:0xc
	v_mov_b32_dpp v239, v243 row_ror:8 row_mask:0xf bank_mask:0xc
	v_mov_b32_dpp v240, v244 row_ror:8 row_mask:0xf bank_mask:0xc
	v_mov_b32_dpp v241, v245 row_ror:8 row_mask:0xf bank_mask:0xc
	v_mov_b32_dpp v242, v48 row_ror:8 row_mask:0xf bank_mask:0x3
	v_mov_b32_dpp v243, v49 row_ror:8 row_mask:0xf bank_mask:0x3
	v_mov_b32_dpp v244, v50 row_ror:8 row_mask:0xf bank_mask:0x3
	v_mov_b32_dpp v245, v51 row_ror:8 row_mask:0xf bank_mask:0x3
	s_add_u32 s88, s96, 0x90000
	s_addc_u32 s89, s97, 0
	global_store_dwordx4 v253, v[238:241], s[88:89]
	s_add_u32 s88, s96, 0x98000
	s_addc_u32 s89, s97, 0
	global_store_dwordx4 v253, v[242:245], s[88:89]
	v_cvt_pk_bf16_f32 v222, v32, v33
	v_cvt_pk_bf16_f32 v223, v34, v35
	v_cvt_pk_bf16_f32 v224, v28, v29
	v_cvt_pk_bf16_f32 v225, v30, v31
	v_cvt_pk_bf16_f32 v226, v24, v25
	v_cvt_pk_bf16_f32 v227, v26, v27
	v_cvt_pk_bf16_f32 v228, v20, v21
	v_cvt_pk_bf16_f32 v229, v22, v23
	v_mov_b32_e32 v32, v222
	v_mov_b32_e32 v33, v223
	v_mov_b32_e32 v34, v224
	v_mov_b32_e32 v35, v225
	v_mov_b32_dpp v222, v226 row_ror:8 row_mask:0xf bank_mask:0xc
	v_mov_b32_dpp v223, v227 row_ror:8 row_mask:0xf bank_mask:0xc
	v_mov_b32_dpp v224, v228 row_ror:8 row_mask:0xf bank_mask:0xc
	v_mov_b32_dpp v225, v229 row_ror:8 row_mask:0xf bank_mask:0xc
	v_mov_b32_dpp v226, v32 row_ror:8 row_mask:0xf bank_mask:0x3
	v_mov_b32_dpp v227, v33 row_ror:8 row_mask:0xf bank_mask:0x3
	v_mov_b32_dpp v228, v34 row_ror:8 row_mask:0xf bank_mask:0x3
	v_mov_b32_dpp v229, v35 row_ror:8 row_mask:0xf bank_mask:0x3
	s_add_u32 s88, s96, 0xa0000
	s_addc_u32 s89, s97, 0
	global_store_dwordx4 v253, v[222:225], s[88:89]
	s_add_u32 s88, s96, 0xa8000
	s_addc_u32 s89, s97, 0
	global_store_dwordx4 v253, v[226:229], s[88:89]
	v_cvt_pk_bf16_f32 v230, v16, v17
	v_cvt_pk_bf16_f32 v231, v18, v19
	v_cvt_pk_bf16_f32 v232, v12, v13
	v_cvt_pk_bf16_f32 v233, v14, v15
	v_cvt_pk_bf16_f32 v234, v8, v9
	v_cvt_pk_bf16_f32 v235, v10, v11
	v_cvt_pk_bf16_f32 v236, v4, v5
	v_cvt_pk_bf16_f32 v237, v6, v7
	v_mov_b32_e32 v16, v230
	v_mov_b32_e32 v17, v231
	v_mov_b32_e32 v18, v232
	v_mov_b32_e32 v19, v233
	v_mov_b32_dpp v230, v234 row_ror:8 row_mask:0xf bank_mask:0xc
	v_mov_b32_dpp v231, v235 row_ror:8 row_mask:0xf bank_mask:0xc
	v_mov_b32_dpp v232, v236 row_ror:8 row_mask:0xf bank_mask:0xc
	v_mov_b32_dpp v233, v237 row_ror:8 row_mask:0xf bank_mask:0xc
	v_mov_b32_dpp v234, v16 row_ror:8 row_mask:0xf bank_mask:0x3
	v_mov_b32_dpp v235, v17 row_ror:8 row_mask:0xf bank_mask:0x3
	v_mov_b32_dpp v236, v18 row_ror:8 row_mask:0xf bank_mask:0x3
	v_mov_b32_dpp v237, v19 row_ror:8 row_mask:0xf bank_mask:0x3
	s_add_u32 s88, s96, 0xb0000
	s_addc_u32 s89, s97, 0
	global_store_dwordx4 v253, v[230:233], s[88:89]
	s_add_u32 s88, s96, 0xb8000
	s_addc_u32 s89, s97, 0
	global_store_dwordx4 v253, v[234:237], s[88:89]
	s_andn2_b64 vcc, exec, s[4:5]
	s_mov_b64 s[4:5], -1
	s_cbranch_vccnz .LBB0_1091
	s_andn2_b64 vcc, exec, s[8:9]
	s_cbranch_vccnz .LBB0_1090
	s_barrier
	s_branch .LBB0_1090

.LBB0_1226:
	s_cmp_le_i32 s84, s0
	s_waitcnt lgkmcnt(0)
	s_cselect_b64 s[2:3], -1, 0
	s_cmp_lt_i32 s0, s85
	s_cselect_b64 s[0:1], -1, 0
	s_and_b64 s[6:7], s[2:3], s[0:1]
	s_andn2_b64 vcc, exec, s[6:7]
	s_cbranch_vccnz .LBB0_1244
	s_mov_b64 s[2:3], s[58:59]
	v_readlane_b32 s1, v254, 2
	s_mov_b32 s14, s57
	v_mov_b32_e32 v1, v0
	v_mov_b32_e32 v4, v0
	s_movk_i32 s12, 0x800
	v_readfirstlane_b32 s18, v4
	s_ashr_i32 s13, s18, 6
	s_cmpk_gt_i32 s14, 0xbff
	s_cbranch_scc1 .LBB0_1244
	v_bfe_i32 v2, v4, 27, 1
	v_lshlrev_b32_e32 v5, 4, v4
	v_lshrrev_b32_e32 v2, 22, v2
	v_add_u32_e32 v2, v5, v2
	v_and_b32_e32 v2, 0xfffffc00, v2
	v_sub_u32_e32 v2, v5, v2
	v_lshrrev_b32_e32 v6, 4, v2
	v_bitop3_b32 v2, v6, v2, 32 bitop3:0x6c
	v_ashrrev_i32_e32 v7, 31, v2
	v_ashrrev_i32_e32 v1, 31, v4
	v_lshrrev_b32_e32 v7, 26, v7
	v_lshrrev_b32_e32 v1, 26, v1
	v_add_u32_e32 v7, v2, v7
	v_add_u32_e32 v1, v4, v1
	v_ashrrev_i32_e32 v8, 6, v7
	v_and_b32_e32 v7, 0xc0, v7
	v_ashrrev_i32_e32 v1, 6, v1
	v_sub_u32_e32 v2, v2, v7
	v_mov_b32_e32 v10, 1
	v_lshlrev_b32_e32 v6, 3, v1
	v_lshlrev_b32_e32 v1, 5, v1
	v_ashrrev_i16_sdwa v2, v10, sext(v2) dst_sel:DWORD dst_unused:UNUSED_PAD src0_sel:DWORD src1_sel:BYTE_0
	v_and_b32_e32 v6, -16, v6
	v_and_b32_e32 v1, 32, v1
	v_bfe_i32 v2, v2, 0, 16
	v_add_u32_e32 v6, v8, v6
	v_and_b32_e32 v8, 3, v8
	s_mov_b32 s0, 0xfffe0
	v_add_lshl_u32 v2, v1, v2, 1
	v_add_u32_e32 v5, 0x2000, v5
	v_lshlrev_b32_e32 v7, 1, v6
	v_lshrrev_b32_e32 v9, 2, v6
	v_and_or_b32 v8, v6, s0, v8
	v_lshl_add_u32 v1, v6, 12, v2
	v_ashrrev_i32_e32 v6, 31, v5
	v_lshrrev_b32_e32 v6, 22, v6
	s_load_dwordx2 s[4:5], s[2:3], 0xe0
	v_and_b32_e32 v7, 24, v7
	v_and_b32_e32 v9, 4, v9
	v_add_u32_e32 v6, v5, v6
	v_or3_b32 v7, v8, v9, v7
	v_ashrrev_i32_e32 v6, 10, v6
	v_lshl_add_u32 v2, v7, 12, v2
	v_lshrrev_b32_e32 v251, 8, v0
	v_lshl_add_u32 v2, v251, 17, v2
	v_mul_i32_i24_e32 v7, 0x400, v6
	v_sub_u32_e32 v5, v5, v7
	v_lshrrev_b32_e32 v7, 4, v5
	s_waitcnt lgkmcnt(0)
	s_add_u32 s15, s4, 0x9800000
	v_bitop3_b32 v5, v7, v5, 32 bitop3:0x6c
	s_addc_u32 s17, s5, 0
	v_ashrrev_i32_e32 v8, 31, v5
	s_add_u32 s33, s4, 0x57c0000
	v_lshrrev_b32_e32 v8, 26, v8
	s_addc_u32 s34, s5, 0
	s_ashr_i32 s35, s14, 31
	v_lshlrev_b32_e32 v7, 3, v6
	v_add_u32_e32 v8, v5, v8
	v_and_b32_e32 v7, -16, v7
	v_ashrrev_i32_e32 v9, 6, v8
	s_lshr_b32 s2, s35, 29
	v_add_u32_e32 v7, v9, v7
	v_and_b32_e32 v9, 3, v9
	s_add_i32 s2, s14, s2
	v_and_or_b32 v9, v7, s0, v9
	s_lshl_b32 s0, s13, 10
	s_ashr_i32 s3, s2, 3
	s_and_b32 s2, s2, -8
	s_ashr_i32 s19, s18, 8
	s_add_i32 s0, s0, 0
	s_sub_i32 s2, s14, s2
	s_cmp_lt_i32 s2, 0
	s_movk_i32 s8, 0x181
	s_cselect_b32 s8, s8, 0x180
	s_mul_i32 s2, s2, s8
	s_add_i32 s2, s2, s3
	s_ashr_i32 s3, s2, 31
	s_lshr_b32 s3, s3, 24
	s_add_i32 s3, s2, s3
	s_ashr_i32 s8, s3, 8
	s_and_b32 s3, s3, 0xff00
	s_sub_i32 s2, s2, s3
	s_sext_i32_i16 s3, s2
	s_bfe_u32 s3, s3, 0x3001c
	s_add_i32 s3, s2, s3
	s_sext_i32_i16 s9, s3
	s_and_b32 s3, s3, 0xfff8
	s_sub_i32 s2, s2, s3
	s_lshl_b32 s8, s8, 3
	s_sext_i32_i16 s2, s2
	v_and_b32_e32 v8, 0xc0, v8
	s_lshr_b32 s10, s9, 3
	s_add_i32 s2, s8, s2
	v_sub_u32_e32 v5, v5, v8
	s_ashr_i32 s3, s2, 31
	s_bfe_i64 s[20:21], s[10:11], 0x100000
	v_lshlrev_b32_e32 v6, 5, v6
	v_ashrrev_i16_sdwa v5, v10, sext(v5) dst_sel:DWORD dst_unused:UNUSED_PAD src0_sel:DWORD src1_sel:BYTE_0
	v_lshlrev_b32_e32 v8, 1, v7
	v_lshrrev_b32_e32 v10, 2, v7
	s_lshl_b64 s[8:9], s[2:3], 20
	s_lshl_b64 s[20:21], s[20:21], 20
	v_and_b32_e32 v6, 32, v6
	v_bfe_i32 v5, v5, 0, 16
	v_and_b32_e32 v8, 24, v8
	v_and_b32_e32 v10, 4, v10
	s_add_u32 s28, s33, s20
	v_or3_b32 v8, v9, v10, v8
	v_add_lshl_u32 v5, v6, v5, 1
	s_addc_u32 s29, s34, s21
	s_add_i32 s40, s0, 0x10000
	s_mov_b32 m0, s40
	s_nop 0
	global_load_lds_dwordx4 v2, s[28:29]
	s_add_i32 s41, s0, 0x12000
	v_lshl_add_u32 v135, v8, 12, v5
	v_lshl_add_u32 v135, v251, 17, v135
	v_add_u32_e32 v135, 0x40000, v135
	s_mov_b32 m0, s41
	s_nop 0
	global_load_lds_dwordx4 v135, s[28:29]
	s_add_u32 s20, s28, 0x20000
	s_addc_u32 s21, s29, 0
	s_add_i32 s42, s0, 0x14000
	s_mov_b32 m0, s42
	s_nop 0
	global_load_lds_dwordx4 v2, s[20:21]
	s_add_i32 s43, s0, 0x16000
	s_mov_b32 m0, s43
	s_nop 0
	global_load_lds_dwordx4 v135, s[20:21]
	s_add_u32 s30, s15, s8
	s_addc_u32 s31, s17, s9
	s_mov_b32 m0, s0
	s_nop 0
	global_load_lds_dwordx4 v1, s[30:31]
	s_add_i32 s48, s0, 0x2000
	v_lshl_add_u32 v134, v7, 12, v5
	s_mov_b32 m0, s48
	s_nop 0
	global_load_lds_dwordx4 v134, s[30:31]
	s_add_u32 s8, s30, 0x80000
	s_addc_u32 s9, s31, 0
	s_add_i32 s49, s0, 0x4000
	s_mov_b32 m0, s49
	s_nop 0
	global_load_lds_dwordx4 v1, s[8:9]
	s_add_i32 s50, s0, 0x6000
	s_mov_b32 m0, s50
	s_nop 0
	global_load_lds_dwordx4 v134, s[8:9]
	s_cmp_eq_u32 s19, 1
	s_cselect_b64 s[8:9], -1, 0
	s_cmp_lg_u32 s19, 1
	s_cbranch_scc1 .LBB0_1230
	s_barrier
.LBB0_1230:
	s_sext_i32_i16 s3, s10
	s_add_u32 s10, s4, 0x1d000000
	s_addc_u32 s11, s5, 0
	s_ashr_i32 s4, s12, 31
	v_lshrrev_b32_e32 v6, 1, v4
	s_lshr_b32 s4, s4, 26
	v_and_b32_e32 v6, 24, v6
	v_and_b32_e32 v5, 15, v4
	s_add_i32 s4, s12, s4
	v_lshlrev_b32_e32 v7, 1, v6
	v_lshlrev_b32_e32 v4, 2, v4
	s_ashr_i32 s52, s4, 6
	v_lshl_or_b32 v136, s19, 6, v5
	v_lshl_or_b32 v5, v5, 6, v7
	s_lshl_b32 s4, s19, 13
	v_and_b32_e32 v4, 32, v4
	v_bitop3_b32 v7, v5, s4, v4 bitop3:0xde
	s_lshl_b32 s4, s13, 5
	s_and_b32 s20, s4, 0x60
	s_ashr_i32 s51, s1, 31
	s_lshl_b32 s4, s20, 7
	v_bitop3_b32 v4, v5, s4, v4 bitop3:0xde
	s_add_u32 s4, s28, 0x80
	s_waitcnt vmcnt(2)
	s_barrier
	s_addc_u32 s5, s29, 0
	s_add_i32 s53, s0, 0x18000
	s_mov_b32 m0, s53
	s_nop 0
	global_load_lds_dwordx4 v2, s[4:5]
	s_add_i32 s54, s0, 0x1a000
	s_mov_b32 m0, s54
	s_nop 0
	global_load_lds_dwordx4 v135, s[4:5]
	s_add_u32 s4, s30, 0x80
	s_addc_u32 s5, s31, 0
	s_add_i32 s55, s0, 0x8000
	s_mov_b32 m0, s55
	s_nop 0
	global_load_lds_dwordx4 v1, s[4:5]
	s_add_i32 s56, s0, 0xa000
	s_mov_b32 m0, s56
	s_nop 0
	global_load_lds_dwordx4 v134, s[4:5]
	s_add_u32 s4, s28, 0x20080
	s_addc_u32 s5, s29, 0
	s_add_i32 s57, s0, 0x1c000
	s_mov_b32 m0, s57
	s_nop 0
	global_load_lds_dwordx4 v2, s[4:5]
	s_add_i32 s58, s0, 0x1e000
	s_mov_b32 m0, s58
	s_nop 0
	global_load_lds_dwordx4 v135, s[4:5]
	s_cmp_gt_i32 s12, 63
	s_waitcnt vmcnt(6)
	s_cselect_b64 s[12:13], -1, 0
	s_add_i32 s59, s52, -2
	s_add_i32 s60, s0, 0xc000
	s_cmpk_lt_u32 s18, 0x100
	s_cselect_b64 s[18:19], -1, 0
	s_add_i32 s61, s0, 0xe000
	v_or_b32_e32 v137, s20, v6
	s_mov_b32 s62, 0
	v_add_u32_e32 v138, 0, v4
	v_add_u32_e32 v139, 0, v7
	s_barrier
	v_and_b32_e32 v253, 0x47, v136
	v_lshlrev_b32_e32 v253, 14, v253
	v_and_b32_e32 v252, 0x60, v137
	v_lshl_add_u32 v253, v252, 2, v253
	v_bfe_u32 v252, v137, 3, 2
	v_lshl_add_u32 v253, v252, 4, v253
	v_bfe_u32 v252, v136, 3, 1
	v_lshl_add_u32 v253, v252, 6, v253
	s_branch .LBB0_1233

.LBB0_1237:
	v_add_u32_e32 v132, 0x10000, v138
	ds_read_b128 v[140:143], v132
	ds_read_b128 v[144:147], v132 offset:1024
	ds_read_b128 v[148:151], v132 offset:2048
	ds_read_b128 v[152:155], v132 offset:3072
	v_add_u32_e32 v132, 0x14000, v138
	ds_read_b128 v[156:159], v132
	ds_read_b128 v[160:163], v132 offset:1024
	ds_read_b128 v[164:167], v132 offset:2048
	ds_read_b128 v[168:171], v132 offset:3072
	s_add_i32 s69, s28, 2
	s_cmp_eq_u32 s59, s28
	s_cselect_b32 s38, s23, s65
	s_cselect_b32 s39, s21, s66
	s_cselect_b32 s30, s64, s67
	s_cselect_b32 s31, s63, s68
	s_add_u32 s28, s38, 0x80
	s_addc_u32 s29, s39, 0
	ds_read_b128 v[172:175], v139
	ds_read_b128 v[176:179], v139 offset:1024
	ds_read_b128 v[180:183], v139 offset:2048
	ds_read_b128 v[184:187], v139 offset:3072
	ds_read_b128 v[188:191], v139 offset:4096
	ds_read_b128 v[192:195], v139 offset:5120
	ds_read_b128 v[196:199], v139 offset:6144
	ds_read_b128 v[202:205], v139 offset:7168
	s_add_u32 s70, s65, 0x7ff80
	s_addc_u32 s71, s66, 0
	s_mov_b32 m0, s60
	s_nop 0
	global_load_lds_dwordx4 v1, s[70:71]
	s_mov_b32 m0, s61
	s_nop 0
	global_load_lds_dwordx4 v134, s[70:71]
	s_waitcnt vmcnt(8)
	s_waitcnt lgkmcnt(0)
	s_barrier
	s_setprio 1
	s_waitcnt lgkmcnt(7)
	v_mfma_f32_16x16x32_bf16 v[124:127], v[140:143], v[172:175], v[124:127]
	v_mfma_f32_16x16x32_bf16 v[128:131], v[148:151], v[172:175], v[128:131]
	s_waitcnt lgkmcnt(5)
	v_mfma_f32_16x16x32_bf16 v[112:115], v[140:143], v[180:183], v[112:115]
	v_mfma_f32_16x16x32_bf16 v[108:111], v[148:151], v[180:183], v[108:111]
	s_waitcnt lgkmcnt(3)
	v_mfma_f32_16x16x32_bf16 v[96:99], v[140:143], v[188:191], v[96:99]
	v_mfma_f32_16x16x32_bf16 v[92:95], v[148:151], v[188:191], v[92:95]
	s_waitcnt lgkmcnt(1)
	v_mfma_f32_16x16x32_bf16 v[80:83], v[140:143], v[196:199], v[80:83]
	v_mfma_f32_16x16x32_bf16 v[76:79], v[148:151], v[196:199], v[76:79]
	v_mfma_f32_16x16x32_bf16 v[124:127], v[144:147], v[176:179], v[124:127]
	v_mfma_f32_16x16x32_bf16 v[128:131], v[152:155], v[176:179], v[128:131]
	v_mfma_f32_16x16x32_bf16 v[112:115], v[144:147], v[184:187], v[112:115]
	v_mfma_f32_16x16x32_bf16 v[108:111], v[152:155], v[184:187], v[108:111]
	v_mfma_f32_16x16x32_bf16 v[96:99], v[144:147], v[192:195], v[96:99]
	v_mfma_f32_16x16x32_bf16 v[92:95], v[152:155], v[192:195], v[92:95]
	s_waitcnt lgkmcnt(0)
	v_mfma_f32_16x16x32_bf16 v[80:83], v[144:147], v[202:205], v[80:83]
	v_mfma_f32_16x16x32_bf16 v[76:79], v[152:155], v[202:205], v[76:79]
	s_setprio 0
	s_setprio 1
	v_mfma_f32_16x16x32_bf16 v[120:123], v[156:159], v[172:175], v[120:123]
	v_mfma_f32_16x16x32_bf16 v[116:119], v[164:167], v[172:175], v[116:119]
	v_mfma_f32_16x16x32_bf16 v[104:107], v[156:159], v[180:183], v[104:107]
	v_mfma_f32_16x16x32_bf16 v[100:103], v[164:167], v[180:183], v[100:103]
	v_mfma_f32_16x16x32_bf16 v[88:91], v[156:159], v[188:191], v[88:91]
	v_mfma_f32_16x16x32_bf16 v[84:87], v[164:167], v[188:191], v[84:87]
	v_mfma_f32_16x16x32_bf16 v[72:75], v[156:159], v[196:199], v[72:75]
	v_mfma_f32_16x16x32_bf16 v[68:71], v[164:167], v[196:199], v[68:71]
	v_mfma_f32_16x16x32_bf16 v[120:123], v[160:163], v[176:179], v[120:123]
	v_mfma_f32_16x16x32_bf16 v[116:119], v[168:171], v[176:179], v[116:119]
	v_mfma_f32_16x16x32_bf16 v[104:107], v[160:163], v[184:187], v[104:107]
	v_mfma_f32_16x16x32_bf16 v[100:103], v[168:171], v[184:187], v[100:103]
	v_mfma_f32_16x16x32_bf16 v[88:91], v[160:163], v[192:195], v[88:91]
	v_mfma_f32_16x16x32_bf16 v[84:87], v[168:171], v[192:195], v[84:87]
	v_mfma_f32_16x16x32_bf16 v[72:75], v[160:163], v[202:205], v[72:75]
	v_mfma_f32_16x16x32_bf16 v[68:71], v[168:171], v[202:205], v[68:71]
	s_setprio 0
	s_barrier
	ds_read_b128 v[172:175], v139 offset:16384
	ds_read_b128 v[176:179], v139 offset:17408
	ds_read_b128 v[180:183], v139 offset:18432
	ds_read_b128 v[184:187], v139 offset:19456
	ds_read_b128 v[188:191], v139 offset:20480
	ds_read_b128 v[192:195], v139 offset:21504
	ds_read_b128 v[196:199], v139 offset:22528
	ds_read_b128 v[202:205], v139 offset:23552
	s_mov_b32 m0, s40
	s_nop 0
	global_load_lds_dwordx4 v2, s[30:31]
	s_mov_b32 m0, s41
	s_nop 0
	global_load_lds_dwordx4 v135, s[30:31]
	s_add_u32 s70, s30, 0x20000
	s_addc_u32 s71, s31, 0
	s_mov_b32 m0, s42
	s_nop 0
	global_load_lds_dwordx4 v2, s[70:71]
	s_mov_b32 m0, s43
	s_nop 0
	global_load_lds_dwordx4 v135, s[70:71]
	s_mov_b32 m0, s0
	s_nop 0
	global_load_lds_dwordx4 v1, s[38:39]
	s_mov_b32 m0, s48
	s_nop 0
	global_load_lds_dwordx4 v134, s[38:39]
	s_waitcnt vmcnt(8)
	s_waitcnt lgkmcnt(0)
	s_barrier
	s_setprio 1
	s_waitcnt lgkmcnt(7)
	v_mfma_f32_16x16x32_bf16 v[64:67], v[140:143], v[172:175], v[64:67]
	v_mfma_f32_16x16x32_bf16 v[60:63], v[148:151], v[172:175], v[60:63]
	s_waitcnt lgkmcnt(5)
	v_mfma_f32_16x16x32_bf16 v[48:51], v[140:143], v[180:183], v[48:51]
	v_mfma_f32_16x16x32_bf16 v[44:47], v[148:151], v[180:183], v[44:47]
	s_waitcnt lgkmcnt(3)
	v_mfma_f32_16x16x32_bf16 v[32:35], v[140:143], v[188:191], v[32:35]
	v_mfma_f32_16x16x32_bf16 v[28:31], v[148:151], v[188:191], v[28:31]
	s_waitcnt lgkmcnt(1)
	v_mfma_f32_16x16x32_bf16 v[16:19], v[140:143], v[196:199], v[16:19]
	v_mfma_f32_16x16x32_bf16 v[12:15], v[148:151], v[196:199], v[12:15]
	v_mfma_f32_16x16x32_bf16 v[64:67], v[144:147], v[176:179], v[64:67]
	v_mfma_f32_16x16x32_bf16 v[60:63], v[152:155], v[176:179], v[60:63]
	v_mfma_f32_16x16x32_bf16 v[48:51], v[144:147], v[184:187], v[48:51]
	v_mfma_f32_16x16x32_bf16 v[44:47], v[152:155], v[184:187], v[44:47]
	v_mfma_f32_16x16x32_bf16 v[32:35], v[144:147], v[192:195], v[32:35]
	v_mfma_f32_16x16x32_bf16 v[28:31], v[152:155], v[192:195], v[28:31]
	s_waitcnt lgkmcnt(0)
	v_mfma_f32_16x16x32_bf16 v[16:19], v[144:147], v[202:205], v[16:19]
	v_mfma_f32_16x16x32_bf16 v[12:15], v[152:155], v[202:205], v[12:15]
	s_setprio 0
	s_setprio 1
	v_mfma_f32_16x16x32_bf16 v[56:59], v[156:159], v[172:175], v[56:59]
	v_mfma_f32_16x16x32_bf16 v[52:55], v[164:167], v[172:175], v[52:55]
	v_mfma_f32_16x16x32_bf16 v[40:43], v[156:159], v[180:183], v[40:43]
	v_mfma_f32_16x16x32_bf16 v[36:39], v[164:167], v[180:183], v[36:39]
	v_mfma_f32_16x16x32_bf16 v[24:27], v[156:159], v[188:191], v[24:27]
	v_mfma_f32_16x16x32_bf16 v[20:23], v[164:167], v[188:191], v[20:23]
	v_mfma_f32_16x16x32_bf16 v[8:11], v[156:159], v[196:199], v[8:11]
	v_mfma_f32_16x16x32_bf16 v[4:7], v[164:167], v[196:199], v[4:7]
	v_mfma_f32_16x16x32_bf16 v[56:59], v[160:163], v[176:179], v[56:59]
	v_mfma_f32_16x16x32_bf16 v[52:55], v[168:171], v[176:179], v[52:55]
	v_mfma_f32_16x16x32_bf16 v[40:43], v[160:163], v[184:187], v[40:43]
	v_mfma_f32_16x16x32_bf16 v[36:39], v[168:171], v[184:187], v[36:39]
	v_mfma_f32_16x16x32_bf16 v[24:27], v[160:163], v[192:195], v[24:27]
	v_mfma_f32_16x16x32_bf16 v[20:23], v[168:171], v[192:195], v[20:23]
	v_mfma_f32_16x16x32_bf16 v[8:11], v[160:163], v[202:205], v[8:11]
	v_mfma_f32_16x16x32_bf16 v[4:7], v[168:171], v[202:205], v[4:7]
	s_setprio 0
	s_barrier
	v_add_u32_e32 v132, 0x18000, v138
	ds_read_b128 v[140:143], v132
	ds_read_b128 v[144:147], v132 offset:1024
	ds_read_b128 v[148:151], v132 offset:2048
	ds_read_b128 v[152:155], v132 offset:3072
	v_add_u32_e32 v132, 0x1c000, v138
	ds_read_b128 v[156:159], v132
	ds_read_b128 v[160:163], v132 offset:1024
	ds_read_b128 v[164:167], v132 offset:2048
	ds_read_b128 v[168:171], v132 offset:3072
	ds_read_b128 v[172:175], v139 offset:32768
	ds_read_b128 v[176:179], v139 offset:33792
	ds_read_b128 v[180:183], v139 offset:34816
	ds_read_b128 v[184:187], v139 offset:35840
	ds_read_b128 v[188:191], v139 offset:36864
	ds_read_b128 v[192:195], v139 offset:37888
	ds_read_b128 v[196:199], v139 offset:38912
	ds_read_b128 v[202:205], v139 offset:39936
	s_add_u32 s38, s38, 0x80000
	s_addc_u32 s39, s39, 0
	s_mov_b32 m0, s49
	s_nop 0
	global_load_lds_dwordx4 v1, s[38:39]
	s_mov_b32 m0, s50
	s_nop 0
	global_load_lds_dwordx4 v134, s[38:39]
	s_waitcnt vmcnt(8)
	s_waitcnt lgkmcnt(0)
	s_barrier
	s_setprio 1
	s_waitcnt lgkmcnt(7)
	v_mfma_f32_16x16x32_bf16 v[124:127], v[140:143], v[172:175], v[124:127]
	v_mfma_f32_16x16x32_bf16 v[128:131], v[148:151], v[172:175], v[128:131]
	s_waitcnt lgkmcnt(5)
	v_mfma_f32_16x16x32_bf16 v[112:115], v[140:143], v[180:183], v[112:115]
	v_mfma_f32_16x16x32_bf16 v[108:111], v[148:151], v[180:183], v[108:111]
	s_waitcnt lgkmcnt(3)
	v_mfma_f32_16x16x32_bf16 v[96:99], v[140:143], v[188:191], v[96:99]
	v_mfma_f32_16x16x32_bf16 v[92:95], v[148:151], v[188:191], v[92:95]
	s_waitcnt lgkmcnt(1)
	v_mfma_f32_16x16x32_bf16 v[80:83], v[140:143], v[196:199], v[80:83]
	v_mfma_f32_16x16x32_bf16 v[76:79], v[148:151], v[196:199], v[76:79]
	v_mfma_f32_16x16x32_bf16 v[124:127], v[144:147], v[176:179], v[124:127]
	v_mfma_f32_16x16x32_bf16 v[128:131], v[152:155], v[176:179], v[128:131]
	v_mfma_f32_16x16x32_bf16 v[112:115], v[144:147], v[184:187], v[112:115]
	v_mfma_f32_16x16x32_bf16 v[108:111], v[152:155], v[184:187], v[108:111]
	v_mfma_f32_16x16x32_bf16 v[96:99], v[144:147], v[192:195], v[96:99]
	v_mfma_f32_16x16x32_bf16 v[92:95], v[152:155], v[192:195], v[92:95]
	s_waitcnt lgkmcnt(0)
	v_mfma_f32_16x16x32_bf16 v[80:83], v[144:147], v[202:205], v[80:83]
	v_mfma_f32_16x16x32_bf16 v[76:79], v[152:155], v[202:205], v[76:79]
	s_setprio 0
	s_setprio 1
	v_mfma_f32_16x16x32_bf16 v[120:123], v[156:159], v[172:175], v[120:123]
	v_mfma_f32_16x16x32_bf16 v[116:119], v[164:167], v[172:175], v[116:119]
	v_mfma_f32_16x16x32_bf16 v[104:107], v[156:159], v[180:183], v[104:107]
	v_mfma_f32_16x16x32_bf16 v[100:103], v[164:167], v[180:183], v[100:103]
	v_mfma_f32_16x16x32_bf16 v[88:91], v[156:159], v[188:191], v[88:91]
	v_mfma_f32_16x16x32_bf16 v[84:87], v[164:167], v[188:191], v[84:87]
	v_mfma_f32_16x16x32_bf16 v[72:75], v[156:159], v[196:199], v[72:75]
	v_mfma_f32_16x16x32_bf16 v[68:71], v[164:167], v[196:199], v[68:71]
	v_mfma_f32_16x16x32_bf16 v[120:123], v[160:163], v[176:179], v[120:123]
	v_mfma_f32_16x16x32_bf16 v[116:119], v[168:171], v[176:179], v[116:119]
	v_mfma_f32_16x16x32_bf16 v[104:107], v[160:163], v[184:187], v[104:107]
	v_mfma_f32_16x16x32_bf16 v[100:103], v[168:171], v[184:187], v[100:103]
	v_mfma_f32_16x16x32_bf16 v[88:91], v[160:163], v[192:195], v[88:91]
	v_mfma_f32_16x16x32_bf16 v[84:87], v[168:171], v[192:195], v[84:87]
	v_mfma_f32_16x16x32_bf16 v[72:75], v[160:163], v[202:205], v[72:75]
	v_mfma_f32_16x16x32_bf16 v[68:71], v[168:171], v[202:205], v[68:71]
	s_setprio 0
	s_barrier
	ds_read_b128 v[172:175], v139 offset:49152
	ds_read_b128 v[176:179], v139 offset:50176
	ds_read_b128 v[180:183], v139 offset:51200
	ds_read_b128 v[184:187], v139 offset:52224
	ds_read_b128 v[188:191], v139 offset:53248
	ds_read_b128 v[192:195], v139 offset:54272
	ds_read_b128 v[196:199], v139 offset:55296
	ds_read_b128 v[202:205], v139 offset:56320
	s_add_u32 s38, s30, 0x80
	s_addc_u32 s39, s31, 0
	s_mov_b32 m0, s53
	s_nop 0
	global_load_lds_dwordx4 v2, s[38:39]
	s_add_u32 s30, s30, 0x20080
	s_mov_b32 m0, s54
	s_nop 0
	global_load_lds_dwordx4 v135, s[38:39]
	s_addc_u32 s31, s31, 0
	s_mov_b32 m0, s57
	s_nop 0
	global_load_lds_dwordx4 v2, s[30:31]
	s_mov_b32 m0, s58
	s_nop 0
	global_load_lds_dwordx4 v135, s[30:31]
	s_mov_b32 m0, s55
	s_nop 0
	global_load_lds_dwordx4 v1, s[28:29]
	s_mov_b32 m0, s56
	s_nop 0
	global_load_lds_dwordx4 v134, s[28:29]
	s_waitcnt vmcnt(8)
	s_waitcnt lgkmcnt(0)
	s_barrier
	s_setprio 1
	s_waitcnt lgkmcnt(7)
	v_mfma_f32_16x16x32_bf16 v[64:67], v[140:143], v[172:175], v[64:67]
	v_mfma_f32_16x16x32_bf16 v[60:63], v[148:151], v[172:175], v[60:63]
	s_waitcnt lgkmcnt(5)
	v_mfma_f32_16x16x32_bf16 v[48:51], v[140:143], v[180:183], v[48:51]
	v_mfma_f32_16x16x32_bf16 v[44:47], v[148:151], v[180:183], v[44:47]
	s_waitcnt lgkmcnt(3)
	v_mfma_f32_16x16x32_bf16 v[32:35], v[140:143], v[188:191], v[32:35]
	v_mfma_f32_16x16x32_bf16 v[28:31], v[148:151], v[188:191], v[28:31]
	s_waitcnt lgkmcnt(1)
	v_mfma_f32_16x16x32_bf16 v[16:19], v[140:143], v[196:199], v[16:19]
	v_mfma_f32_16x16x32_bf16 v[12:15], v[148:151], v[196:199], v[12:15]
	v_mfma_f32_16x16x32_bf16 v[64:67], v[144:147], v[176:179], v[64:67]
	v_mfma_f32_16x16x32_bf16 v[60:63], v[152:155], v[176:179], v[60:63]
	v_mfma_f32_16x16x32_bf16 v[48:51], v[144:147], v[184:187], v[48:51]
	v_mfma_f32_16x16x32_bf16 v[44:47], v[152:155], v[184:187], v[44:47]
	v_mfma_f32_16x16x32_bf16 v[32:35], v[144:147], v[192:195], v[32:35]
	v_mfma_f32_16x16x32_bf16 v[28:31], v[152:155], v[192:195], v[28:31]
	s_waitcnt lgkmcnt(0)
	v_mfma_f32_16x16x32_bf16 v[16:19], v[144:147], v[202:205], v[16:19]
	v_mfma_f32_16x16x32_bf16 v[12:15], v[152:155], v[202:205], v[12:15]
	s_setprio 0
	s_setprio 1
	v_mfma_f32_16x16x32_bf16 v[56:59], v[156:159], v[172:175], v[56:59]
	v_mfma_f32_16x16x32_bf16 v[52:55], v[164:167], v[172:175], v[52:55]
	v_mfma_f32_16x16x32_bf16 v[40:43], v[156:159], v[180:183], v[40:43]
	v_mfma_f32_16x16x32_bf16 v[36:39], v[164:167], v[180:183], v[36:39]
	v_mfma_f32_16x16x32_bf16 v[24:27], v[156:159], v[188:191], v[24:27]
	v_mfma_f32_16x16x32_bf16 v[20:23], v[164:167], v[188:191], v[20:23]
	v_mfma_f32_16x16x32_bf16 v[8:11], v[156:159], v[196:199], v[8:11]
	v_mfma_f32_16x16x32_bf16 v[4:7], v[164:167], v[196:199], v[4:7]
	v_mfma_f32_16x16x32_bf16 v[56:59], v[160:163], v[176:179], v[56:59]
	v_mfma_f32_16x16x32_bf16 v[52:55], v[168:171], v[176:179], v[52:55]
	v_mfma_f32_16x16x32_bf16 v[40:43], v[160:163], v[184:187], v[40:43]
	v_mfma_f32_16x16x32_bf16 v[36:39], v[168:171], v[184:187], v[36:39]
	v_mfma_f32_16x16x32_bf16 v[24:27], v[160:163], v[192:195], v[24:27]
	v_mfma_f32_16x16x32_bf16 v[20:23], v[168:171], v[192:195], v[20:23]
	v_mfma_f32_16x16x32_bf16 v[8:11], v[160:163], v[202:205], v[8:11]
	v_mfma_f32_16x16x32_bf16 v[4:7], v[168:171], v[202:205], v[4:7]
	s_setprio 0
	s_barrier
	s_add_u32 s65, s65, 0x100
	s_addc_u32 s66, s66, 0
	s_add_u32 s67, s67, 0x100
	s_addc_u32 s68, s68, 0
	s_cmp_ge_i32 s69, s52
	s_mov_b32 s28, s69
	s_cbranch_scc0 .LBB0_1237

.LBB0_1240:
	s_nop 15
	s_nop 7
	s_lshl_b32 s96, s2, 22
	s_lshl_b32 s97, s3, 9
	s_add_u32 s96, s96, s97
	s_add_u32 s96, s10, s96
	s_addc_u32 s97, s11, 0
	v_max_f32_e32 v124, v124, v124
	v_max_f32_e32 v125, v125, v125
	v_max_f32_e32 v126, v126, v126
	v_max_f32_e32 v127, v127, v127
	v_max_f32_e32 v128, v128, v128
	v_max_f32_e32 v129, v129, v129
	v_max_f32_e32 v130, v130, v130
	v_max_f32_e32 v131, v131, v131
	v_max_f32_e32 v120, v120, v120
	v_max_f32_e32 v121, v121, v121
	v_max_f32_e32 v122, v122, v122
	v_max_f32_e32 v123, v123, v123
	v_max_f32_e32 v116, v116, v116
	v_max_f32_e32 v117, v117, v117
	v_max_f32_e32 v118, v118, v118
	v_max_f32_e32 v119, v119, v119
	v_max_f32_e32 v124, 0, v124
	v_max_f32_e32 v125, 0, v125
	v_max_f32_e32 v126, 0, v126
	v_max_f32_e32 v127, 0, v127
	v_max_f32_e32 v128, 0, v128
	v_max_f32_e32 v129, 0, v129
	v_max_f32_e32 v130, 0, v130
	v_max_f32_e32 v131, 0, v131
	v_max_f32_e32 v120, 0, v120
	v_max_f32_e32 v121, 0, v121
	v_max_f32_e32 v122, 0, v122
	v_max_f32_e32 v123, 0, v123
	v_max_f32_e32 v116, 0, v116
	v_max_f32_e32 v117, 0, v117
	v_max_f32_e32 v118, 0, v118
	v_max_f32_e32 v119, 0, v119
	v_mul_f32_e32 v124, v124, v124
	v_mul_f32_e32 v125, v125, v125
	v_mul_f32_e32 v126, v126, v126
	v_mul_f32_e32 v127, v127, v127
	v_mul_f32_e32 v128, v128, v128
	v_mul_f32_e32 v129, v129, v129
	v_mul_f32_e32 v130, v130, v130
	v_mul_f32_e32 v131, v131, v131
	v_mul_f32_e32 v120, v120, v120
	v_mul_f32_e32 v121, v121, v121
	v_mul_f32_e32 v122, v122, v122
	v_mul_f32_e32 v123, v123, v123
	v_mul_f32_e32 v116, v116, v116
	v_mul_f32_e32 v117, v117, v117
	v_mul_f32_e32 v118, v118, v118
	v_mul_f32_e32 v119, v119, v119
	v_cvt_pk_bf16_f32 v222, v124, v125
	v_cvt_pk_bf16_f32 v223, v126, v127
	v_cvt_pk_bf16_f32 v224, v128, v129
	v_cvt_pk_bf16_f32 v225, v130, v131
	v_cvt_pk_bf16_f32 v226, v120, v121
	v_cvt_pk_bf16_f32 v227, v122, v123
	v_cvt_pk_bf16_f32 v228, v116, v117
	v_cvt_pk_bf16_f32 v229, v118, v119
	v_mov_b32_e32 v124, v222
	v_mov_b32_e32 v125, v223
	v_mov_b32_e32 v126, v224
	v_mov_b32_e32 v127, v225
	v_mov_b32_dpp v222, v226 row_ror:8 row_mask:0xf bank_mask:0xc
	v_mov_b32_dpp v223, v227 row_ror:8 row_mask:0xf bank_mask:0xc
	v_mov_b32_dpp v224, v228 row_ror:8 row_mask:0xf bank_mask:0xc
	v_mov_b32_dpp v225, v229 row_ror:8 row_mask:0xf bank_mask:0xc
	v_mov_b32_dpp v226, v124 row_ror:8 row_mask:0xf bank_mask:0x3
	v_mov_b32_dpp v227, v125 row_ror:8 row_mask:0xf bank_mask:0x3
	v_mov_b32_dpp v228, v126 row_ror:8 row_mask:0xf bank_mask:0x3
	v_mov_b32_dpp v229, v127 row_ror:8 row_mask:0xf bank_mask:0x3
	s_add_u32 s88, s96, 0x0
	s_addc_u32 s89, s97, 0
	global_store_dwordx4 v253, v[222:225], s[88:89]
	s_add_u32 s88, s96, 0x20000
	s_addc_u32 s89, s97, 0
	global_store_dwordx4 v253, v[226:229], s[88:89]
	v_max_f32_e32 v112, v112, v112
	v_max_f32_e32 v113, v113, v113
	v_max_f32_e32 v114, v114, v114
	v_max_f32_e32 v115, v115, v115
	v_max_f32_e32 v108, v108, v108
	v_max_f32_e32 v109, v109, v109
	v_max_f32_e32 v110, v110, v110
	v_max_f32_e32 v111, v111, v111
	v_max_f32_e32 v104, v104, v104
	v_max_f32_e32 v105, v105, v105
	v_max_f32_e32 v106, v106, v106
	v_max_f32_e32 v107, v107, v107
	v_max_f32_e32 v100, v100, v100
	v_max_f32_e32 v101, v101, v101
	v_max_f32_e32 v102, v102, v102
	v_max_f32_e32 v103, v103, v103
	v_max_f32_e32 v112, 0, v112
	v_max_f32_e32 v113, 0, v113
	v_max_f32_e32 v114, 0, v114
	v_max_f32_e32 v115, 0, v115
	v_max_f32_e32 v108, 0, v108
	v_max_f32_e32 v109, 0, v109
	v_max_f32_e32 v110, 0, v110
	v_max_f32_e32 v111, 0, v111
	v_max_f32_e32 v104, 0, v104
	v_max_f32_e32 v105, 0, v105
	v_max_f32_e32 v106, 0, v106
	v_max_f32_e32 v107, 0, v107
	v_max_f32_e32 v100, 0, v100
	v_max_f32_e32 v101, 0, v101
	v_max_f32_e32 v102, 0, v102
	v_max_f32_e32 v103, 0, v103
	v_mul_f32_e32 v112, v112, v112
	v_mul_f32_e32 v113, v113, v113
	v_mul_f32_e32 v114, v114, v114
	v_mul_f32_e32 v115, v115, v115
	v_mul_f32_e32 v108, v108, v108
	v_mul_f32_e32 v109, v109, v109
	v_mul_f32_e32 v110, v110, v110
	v_mul_f32_e32 v111, v111, v111
	v_mul_f32_e32 v104, v104, v104
	v_mul_f32_e32 v105, v105, v105
	v_mul_f32_e32 v106, v106, v106
	v_mul_f32_e32 v107, v107, v107
	v_mul_f32_e32 v100, v100, v100
	v_mul_f32_e32 v101, v101, v101
	v_mul_f32_e32 v102, v102, v102
	v_mul_f32_e32 v103, v103, v103
	v_cvt_pk_bf16_f32 v230, v112, v113
	v_cvt_pk_bf16_f32 v231, v114, v115
	v_cvt_pk_bf16_f32 v232, v108, v109
	v_cvt_pk_bf16_f32 v233, v110, v111
	v_cvt_pk_bf16_f32 v234, v104, v105
	v_cvt_pk_bf16_f32 v235, v106, v107
	v_cvt_pk_bf16_f32 v236, v100, v101
	v_cvt_pk_bf16_f32 v237, v102, v103
	v_mov_b32_e32 v112, v230
	v_mov_b32_e32 v113, v231
	v_mov_b32_e32 v114, v232
	v_mov_b32_e32 v115, v233
	v_mov_b32_dpp v230, v234 row_ror:8 row_mask:0xf bank_mask:0xc
	v_mov_b32_dpp v231, v235 row_ror:8 row_mask:0xf bank_mask:0xc
	v_mov_b32_dpp v232, v236 row_ror:8 row_mask:0xf bank_mask:0xc
	v_mov_b32_dpp v233, v237 row_ror:8 row_mask:0xf bank_mask:0xc
	v_mov_b32_dpp v234, v112 row_ror:8 row_mask:0xf bank_mask:0x3
	v_mov_b32_dpp v235, v113 row_ror:8 row_mask:0xf bank_mask:0x3
	v_mov_b32_dpp v236, v114 row_ror:8 row_mask:0xf bank_mask:0x3
	v_mov_b32_dpp v237, v115 row_ror:8 row_mask:0xf bank_mask:0x3
	s_add_u32 s88, s96, 0x40000
	s_addc_u32 s89, s97, 0
	global_store_dwordx4 v253, v[230:233], s[88:89]
	s_add_u32 s88, s96, 0x60000
	s_addc_u32 s89, s97, 0
	global_store_dwordx4 v253, v[234:237], s[88:89]
	v_max_f32_e32 v96, v96, v96
	v_max_f32_e32 v97, v97, v97
	v_max_f32_e32 v98, v98, v98
	v_max_f32_e32 v99, v99, v99
	v_max_f32_e32 v92, v92, v92
	v_max_f32_e32 v93, v93, v93
	v_max_f32_e32 v94, v94, v94
	v_max_f32_e32 v95, v95, v95
	v_max_f32_e32 v88, v88, v88
	v_max_f32_e32 v89, v89, v89
	v_max_f32_e32 v90, v90, v90
	v_max_f32_e32 v91, v91, v91
	v_max_f32_e32 v84, v84, v84
	v_max_f32_e32 v85, v85, v85
	v_max_f32_e32 v86, v86, v86
	v_max_f32_e32 v87, v87, v87
	v_max_f32_e32 v96, 0, v96
	v_max_f32_e32 v97, 0, v97
	v_max_f32_e32 v98, 0, v98
	v_max_f32_e32 v99, 0, v99
	v_max_f32_e32 v92, 0, v92
	v_max_f32_e32 v93, 0, v93
	v_max_f32_e32 v94, 0, v94
	v_max_f32_e32 v95, 0, v95
	v_max_f32_e32 v88, 0, v88
	v_max_f32_e32 v89, 0, v89
	v_max_f32_e32 v90, 0, v90
	v_max_f32_e32 v91, 0, v91
	v_max_f32_e32 v84, 0, v84
	v_max_f32_e32 v85, 0, v85
	v_max_f32_e32 v86, 0, v86
	v_max_f32_e32 v87, 0, v87
	v_mul_f32_e32 v96, v96, v96
	v_mul_f32_e32 v97, v97, v97
	v_mul_f32_e32 v98, v98, v98
	v_mul_f32_e32 v99, v99, v99
	v_mul_f32_e32 v92, v92, v92
	v_mul_f32_e32 v93, v93, v93
	v_mul_f32_e32 v94, v94, v94
	v_mul_f32_e32 v95, v95, v95
	v_mul_f32_e32 v88, v88, v88
	v_mul_f32_e32 v89, v89, v89
	v_mul_f32_e32 v90, v90, v90
	v_mul_f32_e32 v91, v91, v91
	v_mul_f32_e32 v84, v84, v84
	v_mul_f32_e32 v85, v85, v85
	v_mul_f32_e32 v86, v86, v86
	v_mul_f32_e32 v87, v87, v87
	v_cvt_pk_bf16_f32 v238, v96, v97
	v_cvt_pk_bf16_f32 v239, v98, v99
	v_cvt_pk_bf16_f32 v240, v92, v93
	v_cvt_pk_bf16_f32 v241, v94, v95
	v_cvt_pk_bf16_f32 v242, v88, v89
	v_cvt_pk_bf16_f32 v243, v90, v91
	v_cvt_pk_bf16_f32 v244, v84, v85
	v_cvt_pk_bf16_f32 v245, v86, v87
	v_mov_b32_e32 v96, v238
	v_mov_b32_e32 v97, v239
	v_mov_b32_e32 v98, v240
	v_mov_b32_e32 v99, v241
	v_mov_b32_dpp v238, v242 row_ror:8 row_mask:0xf bank_mask:0xc
	v_mov_b32_dpp v239, v243 row_ror:8 row_mask:0xf bank_mask:0xc
	v_mov_b32_dpp v240, v244 row_ror:8 row_mask:0xf bank_mask:0xc
	v_mov_b32_dpp v241, v245 row_ror:8 row_mask:0xf bank_mask:0xc
	v_mov_b32_dpp v242, v96 row_ror:8 row_mask:0xf bank_mask:0x3
	v_mov_b32_dpp v243, v97 row_ror:8 row_mask:0xf bank_mask:0x3
	v_mov_b32_dpp v244, v98 row_ror:8 row_mask:0xf bank_mask:0x3
	v_mov_b32_dpp v245, v99 row_ror:8 row_mask:0xf bank_mask:0x3
	s_add_u32 s88, s96, 0x80000
	s_addc_u32 s89, s97, 0
	global_store_dwordx4 v253, v[238:241], s[88:89]
	s_add_u32 s88, s96, 0xa0000
	s_addc_u32 s89, s97, 0
	global_store_dwordx4 v253, v[242:245], s[88:89]
	v_max_f32_e32 v80, v80, v80
	v_max_f32_e32 v81, v81, v81
	v_max_f32_e32 v82, v82, v82
	v_max_f32_e32 v83, v83, v83
	v_max_f32_e32 v76, v76, v76
	v_max_f32_e32 v77, v77, v77
	v_max_f32_e32 v78, v78, v78
	v_max_f32_e32 v79, v79, v79
	v_max_f32_e32 v72, v72, v72
	v_max_f32_e32 v73, v73, v73
	v_max_f32_e32 v74, v74, v74
	v_max_f32_e32 v75, v75, v75
	v_max_f32_e32 v68, v68, v68
	v_max_f32_e32 v69, v69, v69
	v_max_f32_e32 v70, v70, v70
	v_max_f32_e32 v71, v71, v71
	v_max_f32_e32 v80, 0, v80
	v_max_f32_e32 v81, 0, v81
	v_max_f32_e32 v82, 0, v82
	v_max_f32_e32 v83, 0, v83
	v_max_f32_e32 v76, 0, v76
	v_max_f32_e32 v77, 0, v77
	v_max_f32_e32 v78, 0, v78
	v_max_f32_e32 v79, 0, v79
	v_max_f32_e32 v72, 0, v72
	v_max_f32_e32 v73, 0, v73
	v_max_f32_e32 v74, 0, v74
	v_max_f32_e32 v75, 0, v75
	v_max_f32_e32 v68, 0, v68
	v_max_f32_e32 v69, 0, v69
	v_max_f32_e32 v70, 0, v70
	v_max_f32_e32 v71, 0, v71
	v_mul_f32_e32 v80, v80, v80
	v_mul_f32_e32 v81, v81, v81
	v_mul_f32_e32 v82, v82, v82
	v_mul_f32_e32 v83, v83, v83
	v_mul_f32_e32 v76, v76, v76
	v_mul_f32_e32 v77, v77, v77
	v_mul_f32_e32 v78, v78, v78
	v_mul_f32_e32 v79, v79, v79
	v_mul_f32_e32 v72, v72, v72
	v_mul_f32_e32 v73, v73, v73
	v_mul_f32_e32 v74, v74, v74
	v_mul_f32_e32 v75, v75, v75
	v_mul_f32_e32 v68, v68, v68
	v_mul_f32_e32 v69, v69, v69
	v_mul_f32_e32 v70, v70, v70
	v_mul_f32_e32 v71, v71, v71
	v_cvt_pk_bf16_f32 v222, v80, v81
	v_cvt_pk_bf16_f32 v223, v82, v83
	v_cvt_pk_bf16_f32 v224, v76, v77
	v_cvt_pk_bf16_f32 v225, v78, v79
	v_cvt_pk_bf16_f32 v226, v72, v73
	v_cvt_pk_bf16_f32 v227, v74, v75
	v_cvt_pk_bf16_f32 v228, v68, v69
	v_cvt_pk_bf16_f32 v229, v70, v71
	v_mov_b32_e32 v80, v222
	v_mov_b32_e32 v81, v223
	v_mov_b32_e32 v82, v224
	v_mov_b32_e32 v83, v225
	v_mov_b32_dpp v222, v226 row_ror:8 row_mask:0xf bank_mask:0xc
	v_mov_b32_dpp v223, v227 row_ror:8 row_mask:0xf bank_mask:0xc
	v_mov_b32_dpp v224, v228 row_ror:8 row_mask:0xf bank_mask:0xc
	v_mov_b32_dpp v225, v229 row_ror:8 row_mask:0xf bank_mask:0xc
	v_mov_b32_dpp v226, v80 row_ror:8 row_mask:0xf bank_mask:0x3
	v_mov_b32_dpp v227, v81 row_ror:8 row_mask:0xf bank_mask:0x3
	v_mov_b32_dpp v228, v82 row_ror:8 row_mask:0xf bank_mask:0x3
	v_mov_b32_dpp v229, v83 row_ror:8 row_mask:0xf bank_mask:0x3
	s_add_u32 s88, s96, 0xc0000
	s_addc_u32 s89, s97, 0
	global_store_dwordx4 v253, v[222:225], s[88:89]
	s_add_u32 s88, s96, 0xe0000
	s_addc_u32 s89, s97, 0
	global_store_dwordx4 v253, v[226:229], s[88:89]
	v_max_f32_e32 v64, v64, v64
	v_max_f32_e32 v65, v65, v65
	v_max_f32_e32 v66, v66, v66
	v_max_f32_e32 v67, v67, v67
	v_max_f32_e32 v60, v60, v60
	v_max_f32_e32 v61, v61, v61
	v_max_f32_e32 v62, v62, v62
	v_max_f32_e32 v63, v63, v63
	v_max_f32_e32 v56, v56, v56
	v_max_f32_e32 v57, v57, v57
	v_max_f32_e32 v58, v58, v58
	v_max_f32_e32 v59, v59, v59
	v_max_f32_e32 v52, v52, v52
	v_max_f32_e32 v53, v53, v53
	v_max_f32_e32 v54, v54, v54
	v_max_f32_e32 v55, v55, v55
	v_max_f32_e32 v64, 0, v64
	v_max_f32_e32 v65, 0, v65
	v_max_f32_e32 v66, 0, v66
	v_max_f32_e32 v67, 0, v67
	v_max_f32_e32 v60, 0, v60
	v_max_f32_e32 v61, 0, v61
	v_max_f32_e32 v62, 0, v62
	v_max_f32_e32 v63, 0, v63
	v_max_f32_e32 v56, 0, v56
	v_max_f32_e32 v57, 0, v57
	v_max_f32_e32 v58, 0, v58
	v_max_f32_e32 v59, 0, v59
	v_max_f32_e32 v52, 0, v52
	v_max_f32_e32 v53, 0, v53
	v_max_f32_e32 v54, 0, v54
	v_max_f32_e32 v55, 0, v55
	v_mul_f32_e32 v64, v64, v64
	v_mul_f32_e32 v65, v65, v65
	v_mul_f32_e32 v66, v66, v66
	v_mul_f32_e32 v67, v67, v67
	v_mul_f32_e32 v60, v60, v60
	v_mul_f32_e32 v61, v61, v61
	v_mul_f32_e32 v62, v62, v62
	v_mul_f32_e32 v63, v63, v63
	v_mul_f32_e32 v56, v56, v56
	v_mul_f32_e32 v57, v57, v57
	v_mul_f32_e32 v58, v58, v58
	v_mul_f32_e32 v59, v59, v59
	v_mul_f32_e32 v52, v52, v52
	v_mul_f32_e32 v53, v53, v53
	v_mul_f32_e32 v54, v54, v54
	v_mul_f32_e32 v55, v55, v55
	v_cvt_pk_bf16_f32 v230, v64, v65
	v_cvt_pk_bf16_f32 v231, v66, v67
	v_cvt_pk_bf16_f32 v232, v60, v61
	v_cvt_pk_bf16_f32 v233, v62, v63
	v_cvt_pk_bf16_f32 v234, v56, v57
	v_cvt_pk_bf16_f32 v235, v58, v59
	v_cvt_pk_bf16_f32 v236, v52, v53
	v_cvt_pk_bf16_f32 v237, v54, v55
	v_mov_b32_e32 v64, v230
	v_mov_b32_e32 v65, v231
	v_mov_b32_e32 v66, v232
	v_mov_b32_e32 v67, v233
	v_mov_b32_dpp v230, v234 row_ror:8 row_mask:0xf bank_mask:0xc
	v_mov_b32_dpp v231, v235 row_ror:8 row_mask:0xf bank_mask:0xc
	v_mov_b32_dpp v232, v236 row_ror:8 row_mask:0xf bank_mask:0xc
	v_mov_b32_dpp v233, v237 row_ror:8 row_mask:0xf bank_mask:0xc
	v_mov_b32_dpp v234, v64 row_ror:8 row_mask:0xf bank_mask:0x3
	v_mov_b32_dpp v235, v65 row_ror:8 row_mask:0xf bank_mask:0x3
	v_mov_b32_dpp v236, v66 row_ror:8 row_mask:0xf bank_mask:0x3
	v_mov_b32_dpp v237, v67 row_ror:8 row_mask:0xf bank_mask:0x3
	s_add_u32 s88, s96, 0x200000
	s_addc_u32 s89, s97, 0
	global_store_dwordx4 v253, v[230:233], s[88:89]
	s_add_u32 s88, s96, 0x220000
	s_addc_u32 s89, s97, 0
	global_store_dwordx4 v253, v[234:237], s[88:89]
	v_max_f32_e32 v48, v48, v48
	v_max_f32_e32 v49, v49, v49
	v_max_f32_e32 v50, v50, v50
	v_max_f32_e32 v51, v51, v51
	v_max_f32_e32 v44, v44, v44
	v_max_f32_e32 v45, v45, v45
	v_max_f32_e32 v46, v46, v46
	v_max_f32_e32 v47, v47, v47
	v_max_f32_e32 v40, v40, v40
	v_max_f32_e32 v41, v41, v41
	v_max_f32_e32 v42, v42, v42
	v_max_f32_e32 v43, v43, v43
	v_max_f32_e32 v36, v36, v36
	v_max_f32_e32 v37, v37, v37
	v_max_f32_e32 v38, v38, v38
	v_max_f32_e32 v39, v39, v39
	v_max_f32_e32 v48, 0, v48
	v_max_f32_e32 v49, 0, v49
	v_max_f32_e32 v50, 0, v50
	v_max_f32_e32 v51, 0, v51
	v_max_f32_e32 v44, 0, v44
	v_max_f32_e32 v45, 0, v45
	v_max_f32_e32 v46, 0, v46
	v_max_f32_e32 v47, 0, v47
	v_max_f32_e32 v40, 0, v40
	v_max_f32_e32 v41, 0, v41
	v_max_f32_e32 v42, 0, v42
	v_max_f32_e32 v43, 0, v43
	v_max_f32_e32 v36, 0, v36
	v_max_f32_e32 v37, 0, v37
	v_max_f32_e32 v38, 0, v38
	v_max_f32_e32 v39, 0, v39
	v_mul_f32_e32 v48, v48, v48
	v_mul_f32_e32 v49, v49, v49
	v_mul_f32_e32 v50, v50, v50
	v_mul_f32_e32 v51, v51, v51
	v_mul_f32_e32 v44, v44, v44
	v_mul_f32_e32 v45, v45, v45
	v_mul_f32_e32 v46, v46, v46
	v_mul_f32_e32 v47, v47, v47
	v_mul_f32_e32 v40, v40, v40
	v_mul_f32_e32 v41, v41, v41
	v_mul_f32_e32 v42, v42, v42
	v_mul_f32_e32 v43, v43, v43
	v_mul_f32_e32 v36, v36, v36
	v_mul_f32_e32 v37, v37, v37
	v_mul_f32_e32 v38, v38, v38
	v_mul_f32_e32 v39, v39, v39
	v_cvt_pk_bf16_f32 v238, v48, v49
	v_cvt_pk_bf16_f32 v239, v50, v51
	v_cvt_pk_bf16_f32 v240, v44, v45
	v_cvt_pk_bf16_f32 v241, v46, v47
	v_cvt_pk_bf16_f32 v242, v40, v41
	v_cvt_pk_bf16_f32 v243, v42, v43
	v_cvt_pk_bf16_f32 v244, v36, v37
	v_cvt_pk_bf16_f32 v245, v38, v39
	v_mov_b32_e32 v48, v238
	v_mov_b32_e32 v49, v239
	v_mov_b32_e32 v50, v240
	v_mov_b32_e32 v51, v241
	v_mov_b32_dpp v238, v242 row_ror:8 row_mask:0xf bank_mask:0xc
	v_mov_b32_dpp v239, v243 row_ror:8 row_mask:0xf bank_mask:0xc
	v_mov_b32_dpp v240, v244 row_ror:8 row_mask:0xf bank_mask:0xc
	v_mov_b32_dpp v241, v245 row_ror:8 row_mask:0xf bank_mask:0xc
	v_mov_b32_dpp v242, v48 row_ror:8 row_mask:0xf bank_mask:0x3
	v_mov_b32_dpp v243, v49 row_ror:8 row_mask:0xf bank_mask:0x3
	v_mov_b32_dpp v244, v50 row_ror:8 row_mask:0xf bank_mask:0x3
	v_mov_b32_dpp v245, v51 row_ror:8 row_mask:0xf bank_mask:0x3
	s_add_u32 s88, s96, 0x240000
	s_addc_u32 s89, s97, 0
	global_store_dwordx4 v253, v[238:241], s[88:89]
	s_add_u32 s88, s96, 0x260000
	s_addc_u32 s89, s97, 0
	global_store_dwordx4 v253, v[242:245], s[88:89]
	v_max_f32_e32 v32, v32, v32
	v_max_f32_e32 v33, v33, v33
	v_max_f32_e32 v34, v34, v34
	v_max_f32_e32 v35, v35, v35
	v_max_f32_e32 v28, v28, v28
	v_max_f32_e32 v29, v29, v29
	v_max_f32_e32 v30, v30, v30
	v_max_f32_e32 v31, v31, v31
	v_max_f32_e32 v24, v24, v24
	v_max_f32_e32 v25, v25, v25
	v_max_f32_e32 v26, v26, v26
	v_max_f32_e32 v27, v27, v27
	v_max_f32_e32 v20, v20, v20
	v_max_f32_e32 v21, v21, v21
	v_max_f32_e32 v22, v22, v22
	v_max_f32_e32 v23, v23, v23
	v_max_f32_e32 v32, 0, v32
	v_max_f32_e32 v33, 0, v33
	v_max_f32_e32 v34, 0, v34
	v_max_f32_e32 v35, 0, v35
	v_max_f32_e32 v28, 0, v28
	v_max_f32_e32 v29, 0, v29
	v_max_f32_e32 v30, 0, v30
	v_max_f32_e32 v31, 0, v31
	v_max_f32_e32 v24, 0, v24
	v_max_f32_e32 v25, 0, v25
	v_max_f32_e32 v26, 0, v26
	v_max_f32_e32 v27, 0, v27
	v_max_f32_e32 v20, 0, v20
	v_max_f32_e32 v21, 0, v21
	v_max_f32_e32 v22, 0, v22
	v_max_f32_e32 v23, 0, v23
	v_mul_f32_e32 v32, v32, v32
	v_mul_f32_e32 v33, v33, v33
	v_mul_f32_e32 v34, v34, v34
	v_mul_f32_e32 v35, v35, v35
	v_mul_f32_e32 v28, v28, v28
	v_mul_f32_e32 v29, v29, v29
	v_mul_f32_e32 v30, v30, v30
	v_mul_f32_e32 v31, v31, v31
	v_mul_f32_e32 v24, v24, v24
	v_mul_f32_e32 v25, v25, v25
	v_mul_f32_e32 v26, v26, v26
	v_mul_f32_e32 v27, v27, v27
	v_mul_f32_e32 v20, v20, v20
	v_mul_f32_e32 v21, v21, v21
	v_mul_f32_e32 v22, v22, v22
	v_mul_f32_e32 v23, v23, v23
	v_cvt_pk_bf16_f32 v222, v32, v33
	v_cvt_pk_bf16_f32 v223, v34, v35
	v_cvt_pk_bf16_f32 v224, v28, v29
	v_cvt_pk_bf16_f32 v225, v30, v31
	v_cvt_pk_bf16_f32 v226, v24, v25
	v_cvt_pk_bf16_f32 v227, v26, v27
	v_cvt_pk_bf16_f32 v228, v20, v21
	v_cvt_pk_bf16_f32 v229, v22, v23
	v_mov_b32_e32 v32, v222
	v_mov_b32_e32 v33, v223
	v_mov_b32_e32 v34, v224
	v_mov_b32_e32 v35, v225
	v_mov_b32_dpp v222, v226 row_ror:8 row_mask:0xf bank_mask:0xc
	v_mov_b32_dpp v223, v227 row_ror:8 row_mask:0xf bank_mask:0xc
	v_mov_b32_dpp v224, v228 row_ror:8 row_mask:0xf bank_mask:0xc
	v_mov_b32_dpp v225, v229 row_ror:8 row_mask:0xf bank_mask:0xc
	v_mov_b32_dpp v226, v32 row_ror:8 row_mask:0xf bank_mask:0x3
	v_mov_b32_dpp v227, v33 row_ror:8 row_mask:0xf bank_mask:0x3
	v_mov_b32_dpp v228, v34 row_ror:8 row_mask:0xf bank_mask:0x3
	v_mov_b32_dpp v229, v35 row_ror:8 row_mask:0xf bank_mask:0x3
	s_add_u32 s88, s96, 0x280000
	s_addc_u32 s89, s97, 0
	global_store_dwordx4 v253, v[222:225], s[88:89]
	s_add_u32 s88, s96, 0x2a0000
	s_addc_u32 s89, s97, 0
	global_store_dwordx4 v253, v[226:229], s[88:89]
	v_max_f32_e32 v16, v16, v16
	v_max_f32_e32 v17, v17, v17
	v_max_f32_e32 v18, v18, v18
	v_max_f32_e32 v19, v19, v19
	v_max_f32_e32 v12, v12, v12
	v_max_f32_e32 v13, v13, v13
	v_max_f32_e32 v14, v14, v14
	v_max_f32_e32 v15, v15, v15
	v_max_f32_e32 v8, v8, v8
	v_max_f32_e32 v9, v9, v9
	v_max_f32_e32 v10, v10, v10
	v_max_f32_e32 v11, v11, v11
	v_max_f32_e32 v4, v4, v4
	v_max_f32_e32 v5, v5, v5
	v_max_f32_e32 v6, v6, v6
	v_max_f32_e32 v7, v7, v7
	v_max_f32_e32 v16, 0, v16
	v_max_f32_e32 v17, 0, v17
	v_max_f32_e32 v18, 0, v18
	v_max_f32_e32 v19, 0, v19
	v_max_f32_e32 v12, 0, v12
	v_max_f32_e32 v13, 0, v13
	v_max_f32_e32 v14, 0, v14
	v_max_f32_e32 v15, 0, v15
	v_max_f32_e32 v8, 0, v8
	v_max_f32_e32 v9, 0, v9
	v_max_f32_e32 v10, 0, v10
	v_max_f32_e32 v11, 0, v11
	v_max_f32_e32 v4, 0, v4
	v_max_f32_e32 v5, 0, v5
	v_max_f32_e32 v6, 0, v6
	v_max_f32_e32 v7, 0, v7
	v_mul_f32_e32 v16, v16, v16
	v_mul_f32_e32 v17, v17, v17
	v_mul_f32_e32 v18, v18, v18
	v_mul_f32_e32 v19, v19, v19
	v_mul_f32_e32 v12, v12, v12
	v_mul_f32_e32 v13, v13, v13
	v_mul_f32_e32 v14, v14, v14
	v_mul_f32_e32 v15, v15, v15
	v_mul_f32_e32 v8, v8, v8
	v_mul_f32_e32 v9, v9, v9
	v_mul_f32_e32 v10, v10, v10
	v_mul_f32_e32 v11, v11, v11
	v_mul_f32_e32 v4, v4, v4
	v_mul_f32_e32 v5, v5, v5
	v_mul_f32_e32 v6, v6, v6
	v_mul_f32_e32 v7, v7, v7
	v_cvt_pk_bf16_f32 v230, v16, v17
	v_cvt_pk_bf16_f32 v231, v18, v19
	v_cvt_pk_bf16_f32 v232, v12, v13
	v_cvt_pk_bf16_f32 v233, v14, v15
	v_cvt_pk_bf16_f32 v234, v8, v9
	v_cvt_pk_bf16_f32 v235, v10, v11
	v_cvt_pk_bf16_f32 v236, v4, v5
	v_cvt_pk_bf16_f32 v237, v6, v7
	v_mov_b32_e32 v16, v230
	v_mov_b32_e32 v17, v231
	v_mov_b32_e32 v18, v232
	v_mov_b32_e32 v19, v233
	v_mov_b32_dpp v230, v234 row_ror:8 row_mask:0xf bank_mask:0xc
	v_mov_b32_dpp v231, v235 row_ror:8 row_mask:0xf bank_mask:0xc
	v_mov_b32_dpp v232, v236 row_ror:8 row_mask:0xf bank_mask:0xc
	v_mov_b32_dpp v233, v237 row_ror:8 row_mask:0xf bank_mask:0xc
	v_mov_b32_dpp v234, v16 row_ror:8 row_mask:0xf bank_mask:0x3
	v_mov_b32_dpp v235, v17 row_ror:8 row_mask:0xf bank_mask:0x3
	v_mov_b32_dpp v236, v18 row_ror:8 row_mask:0xf bank_mask:0x3
	v_mov_b32_dpp v237, v19 row_ror:8 row_mask:0xf bank_mask:0x3
	s_add_u32 s88, s96, 0x2c0000
	s_addc_u32 s89, s97, 0
	global_store_dwordx4 v253, v[230:233], s[88:89]
	s_add_u32 s88, s96, 0x2e0000
	s_addc_u32 s89, s97, 0
	global_store_dwordx4 v253, v[234:237], s[88:89]
	s_andn2_b64 vcc, exec, s[4:5]
	s_mov_b64 s[2:3], -1
	s_cbranch_vccnz .LBB0_1232
	s_andn2_b64 vcc, exec, s[8:9]
	s_cbranch_vccnz .LBB0_1231
	s_barrier
	s_branch .LBB0_1231

.LBB0_1298:
	s_cmp_le_i32 s84, s0
	s_cselect_b64 s[0:1], -1, 0
	s_and_b64 s[6:7], s[0:1], s[2:3]
	s_andn2_b64 vcc, exec, s[6:7]
	s_cbranch_vccnz .LBB0_1316
	s_mov_b64 s[2:3], s[58:59]
	s_mov_b32 s0, s57
	v_readlane_b32 s1, v254, 2
	v_mov_b32_e32 v1, v0
	v_mov_b32_e32 v4, v0
	s_movk_i32 s12, 0x2000
	v_readfirstlane_b32 s18, v4
	s_ashr_i32 s13, s18, 6
	s_cmpk_gt_i32 s0, 0x2ff
	s_cbranch_scc1 .LBB0_1316
	v_bfe_i32 v2, v4, 27, 1
	v_lshlrev_b32_e32 v5, 4, v4
	v_lshrrev_b32_e32 v2, 22, v2
	v_add_u32_e32 v2, v5, v2
	v_and_b32_e32 v2, 0xfffffc00, v2
	v_sub_u32_e32 v2, v5, v2
	v_lshrrev_b32_e32 v6, 4, v2
	v_bitop3_b32 v2, v6, v2, 32 bitop3:0x6c
	v_ashrrev_i32_e32 v7, 31, v2
	v_ashrrev_i32_e32 v1, 31, v4
	v_lshrrev_b32_e32 v7, 26, v7
	v_lshrrev_b32_e32 v1, 26, v1
	v_add_u32_e32 v7, v2, v7
	v_add_u32_e32 v1, v4, v1
	v_ashrrev_i32_e32 v8, 6, v7
	v_and_b32_e32 v7, 0xc0, v7
	v_ashrrev_i32_e32 v1, 6, v1
	v_sub_u32_e32 v2, v2, v7
	v_mov_b32_e32 v10, 1
	v_lshlrev_b32_e32 v6, 3, v1
	v_lshlrev_b32_e32 v1, 5, v1
	v_ashrrev_i16_sdwa v2, v10, sext(v2) dst_sel:DWORD dst_unused:UNUSED_PAD src0_sel:DWORD src1_sel:BYTE_0
	v_and_b32_e32 v6, -16, v6
	v_and_b32_e32 v1, 32, v1
	v_bfe_i32 v2, v2, 0, 16
	v_add_u32_e32 v6, v8, v6
	v_and_b32_e32 v8, 3, v8
	s_mov_b32 s4, 0x3ffe0
	v_add_lshl_u32 v2, v1, v2, 1
	v_add_u32_e32 v5, 0x2000, v5
	v_lshlrev_b32_e32 v7, 1, v6
	v_lshrrev_b32_e32 v9, 2, v6
	v_and_or_b32 v8, v6, s4, v8
	v_lshl_add_u32 v1, v6, 14, v2
	v_ashrrev_i32_e32 v6, 31, v5
	v_lshrrev_b32_e32 v6, 22, v6
	v_and_b32_e32 v7, 24, v7
	v_and_b32_e32 v9, 4, v9
	v_add_u32_e32 v6, v5, v6
	v_or3_b32 v7, v8, v9, v7
	v_ashrrev_i32_e32 v6, 10, v6
	v_lshl_add_u32 v2, v7, 14, v2
	v_lshrrev_b32_e32 v251, 8, v0
	v_lshl_add_u32 v2, v251, 19, v2
	v_mul_i32_i24_e32 v7, 0x400, v6
	s_load_dwordx2 s[2:3], s[2:3], 0xe0
	v_sub_u32_e32 v5, v5, v7
	v_lshrrev_b32_e32 v7, 4, v5
	v_bitop3_b32 v5, v7, v5, 32 bitop3:0x6c
	v_ashrrev_i32_e32 v8, 31, v5
	v_lshrrev_b32_e32 v8, 26, v8
	s_waitcnt lgkmcnt(0)
	s_add_u32 s14, s2, 0x1d000000
	v_lshlrev_b32_e32 v7, 3, v6
	v_add_u32_e32 v8, v5, v8
	s_addc_u32 s15, s3, 0
	v_and_b32_e32 v7, -16, v7
	v_ashrrev_i32_e32 v9, 6, v8
	s_add_u32 s17, s2, 0x77c0000
	v_add_u32_e32 v7, v9, v7
	v_and_b32_e32 v9, 3, v9
	s_addc_u32 s33, s3, 0
	s_ashr_i32 s34, s0, 31
	v_and_or_b32 v9, v7, s4, v9
	s_lshl_b32 s4, s13, 10
	s_add_i32 s35, s4, 0
	s_lshr_b32 s4, s34, 29
	s_add_i32 s4, s0, s4
	s_ashr_i32 s5, s4, 3
	s_and_b32 s4, s4, -8
	s_ashr_i32 s19, s18, 8
	s_sub_i32 s4, s0, s4
	s_cmp_lt_i32 s4, 0
	s_movk_i32 s8, 0x61
	s_cselect_b32 s8, s8, 0x60
	s_mul_i32 s4, s4, s8
	s_add_i32 s4, s4, s5
	s_ashr_i32 s5, s4, 31
	s_lshr_b32 s5, s5, 26
	s_add_i32 s5, s4, s5
	s_ashr_i32 s8, s5, 6
	s_and_b32 s5, s5, 0xffc0
	s_sub_i32 s4, s4, s5
	s_bfe_i32 s5, s4, 0x80000
	s_bfe_u32 s5, s5, 0x3000c
	s_add_i32 s5, s4, s5
	s_bfe_i32 s9, s5, 0x80000
	s_and_b32 s5, s5, 0xf8
	s_sub_i32 s4, s4, s5
	s_lshl_b32 s8, s8, 3
	s_sext_i32_i16 s9, s9
	s_sext_i32_i8 s4, s4
	v_and_b32_e32 v8, 0xc0, v8
	s_lshr_b32 s10, s9, 3
	s_add_i32 s22, s8, s4
	v_sub_u32_e32 v5, v5, v8
	s_ashr_i32 s23, s22, 31
	s_bfe_i64 s[4:5], s[10:11], 0x100000
	v_lshlrev_b32_e32 v6, 5, v6
	v_ashrrev_i16_sdwa v5, v10, sext(v5) dst_sel:DWORD dst_unused:UNUSED_PAD src0_sel:DWORD src1_sel:BYTE_0
	v_lshlrev_b32_e32 v8, 1, v7
	v_lshrrev_b32_e32 v10, 2, v7
	s_lshl_b64 s[8:9], s[22:23], 22
	s_lshl_b64 s[4:5], s[4:5], 22
	v_and_b32_e32 v6, 32, v6
	v_bfe_i32 v5, v5, 0, 16
	v_and_b32_e32 v8, 24, v8
	v_and_b32_e32 v10, 4, v10
	s_add_u32 s28, s17, s4
	v_or3_b32 v8, v9, v10, v8
	v_add_lshl_u32 v5, v6, v5, 1
	s_addc_u32 s29, s33, s5
	s_add_i32 s23, s35, 0x10000
	s_mov_b32 m0, s23
	s_nop 0
	global_load_lds_dwordx4 v2, s[28:29]
	v_lshl_add_u32 v133, v8, 14, v5
	v_lshl_add_u32 v133, v251, 19, v133
	v_add_u32_e32 v133, 0x100000, v133
	s_add_i32 s42, s35, 0x12000
	s_mov_b32 m0, s42
	s_nop 0
	global_load_lds_dwordx4 v133, s[28:29]
	s_add_u32 s4, s28, 0x80000
	s_addc_u32 s5, s29, 0
	s_add_i32 s43, s35, 0x14000
	s_mov_b32 m0, s43
	s_nop 0
	global_load_lds_dwordx4 v2, s[4:5]
	s_add_i32 s48, s35, 0x16000
	s_mov_b32 m0, s48
	s_nop 0
	global_load_lds_dwordx4 v133, s[4:5]
	s_add_u32 s30, s14, s8
	s_addc_u32 s31, s15, s9
	s_mov_b32 m0, s35
	s_nop 0
	global_load_lds_dwordx4 v1, s[30:31]
	v_lshl_add_u32 v132, v7, 14, v5
	s_add_i32 s49, s35, 0x2000
	s_mov_b32 m0, s49
	s_nop 0
	global_load_lds_dwordx4 v132, s[30:31]
	s_add_u32 s8, s30, 0x200000
	s_addc_u32 s9, s31, 0
	s_add_i32 s50, s35, 0x4000
	s_mov_b32 m0, s50
	s_nop 0
	global_load_lds_dwordx4 v1, s[8:9]
	s_add_i32 s51, s35, 0x6000
	s_mov_b32 m0, s51
	s_nop 0
	global_load_lds_dwordx4 v132, s[8:9]
	s_cmp_eq_u32 s19, 1
	s_cselect_b64 s[8:9], -1, 0
	s_cmp_lg_u32 s19, 1
	s_cbranch_scc1 .LBB0_1302
	s_barrier
.LBB0_1302:
	s_sext_i32_i8 s64, s10
	s_add_u32 s10, s2, 0x35000000
	s_addc_u32 s11, s3, 0
	s_ashr_i32 s2, s12, 31
	v_lshrrev_b32_e32 v6, 1, v4
	s_lshr_b32 s2, s2, 26
	v_and_b32_e32 v6, 24, v6
	v_and_b32_e32 v5, 15, v4
	s_add_i32 s2, s12, s2
	v_lshlrev_b32_e32 v7, 1, v6
	v_lshlrev_b32_e32 v4, 2, v4
	s_ashr_i32 s53, s2, 6
	v_lshl_or_b32 v134, s19, 6, v5
	v_lshl_or_b32 v5, v5, 6, v7
	s_lshl_b32 s2, s19, 13
	v_and_b32_e32 v4, 32, v4
	v_bitop3_b32 v7, v5, s2, v4 bitop3:0xde
	s_lshl_b32 s2, s13, 5
	s_and_b32 s20, s2, 0x60
	s_ashr_i32 s52, s1, 31
	s_lshl_b32 s2, s20, 7
	v_bitop3_b32 v4, v5, s2, v4 bitop3:0xde
	s_add_u32 s2, s28, 0x80
	s_waitcnt vmcnt(2)
	s_barrier
	s_addc_u32 s3, s29, 0
	s_add_i32 s54, s35, 0x18000
	s_mov_b32 m0, s54
	s_nop 0
	global_load_lds_dwordx4 v2, s[2:3]
	s_add_i32 s55, s35, 0x1a000
	s_mov_b32 m0, s55
	s_nop 0
	global_load_lds_dwordx4 v133, s[2:3]
	s_add_u32 s2, s30, 0x80
	s_addc_u32 s3, s31, 0
	s_add_i32 s56, s35, 0x8000
	s_mov_b32 m0, s56
	s_nop 0
	global_load_lds_dwordx4 v1, s[2:3]
	s_add_i32 s57, s35, 0xa000
	s_mov_b32 m0, s57
	s_nop 0
	global_load_lds_dwordx4 v132, s[2:3]
	s_add_u32 s2, s4, 0x80
	s_addc_u32 s3, s5, 0
	s_add_i32 s58, s35, 0x1c000
	s_mov_b32 m0, s58
	s_nop 0
	global_load_lds_dwordx4 v2, s[2:3]
	s_add_i32 s59, s35, 0x1e000
	s_mov_b32 m0, s59
	s_nop 0
	global_load_lds_dwordx4 v133, s[2:3]
	s_cmp_gt_i32 s12, 63
	s_waitcnt vmcnt(6)
	s_cselect_b64 s[12:13], -1, 0
	s_add_i32 s60, s53, -2
	s_add_i32 s61, s35, 0xc000
	s_cmpk_lt_u32 s18, 0x100
	s_cselect_b64 s[18:19], -1, 0
	s_add_i32 s62, s35, 0xe000
	v_or_b32_e32 v135, s20, v6
	s_mov_b32 s63, 0
	v_add_u32_e32 v136, 0, v4
	v_add_u32_e32 v137, 0, v7
	s_barrier
	v_and_b32_e32 v253, 0x47, v134
	v_lshlrev_b32_e32 v253, 12, v253
	v_and_b32_e32 v252, 0x60, v135
	v_lshl_add_u32 v253, v252, 2, v253
	v_bfe_u32 v252, v135, 3, 2
	v_lshl_add_u32 v253, v252, 4, v253
	v_bfe_u32 v252, v134, 3, 1
	v_lshl_add_u32 v253, v252, 6, v253
	s_branch .LBB0_1305

.LBB0_1309:
	v_add_u32_e32 v150, 0x10000, v136
	v_add_u32_e32 v166, 0x14000, v136
	ds_read_b128 v[138:141], v150
	ds_read_b128 v[142:145], v150 offset:1024
	ds_read_b128 v[146:149], v150 offset:2048
	ds_read_b128 v[150:153], v150 offset:3072
	ds_read_b128 v[154:157], v166
	ds_read_b128 v[158:161], v166 offset:1024
	ds_read_b128 v[162:165], v166 offset:2048
	ds_read_b128 v[166:169], v166 offset:3072
	s_add_i32 s71, s30, 2
	s_cmp_eq_u32 s60, s30
	s_cselect_b32 s40, s21, s67
	s_cselect_b32 s41, s3, s68
	s_cselect_b32 s38, s66, s69
	s_cselect_b32 s39, s65, s70
	s_add_u32 s30, s40, 0x80
	s_addc_u32 s31, s41, 0
	ds_read_b128 v[170:173], v137
	ds_read_b128 v[174:177], v137 offset:1024
	ds_read_b128 v[178:181], v137 offset:2048
	ds_read_b128 v[182:185], v137 offset:3072
	ds_read_b128 v[186:189], v137 offset:4096
	ds_read_b128 v[190:193], v137 offset:5120
	ds_read_b128 v[194:197], v137 offset:6144
	ds_read_b128 v[202:205], v137 offset:7168
	s_mov_b32 m0, s61
	s_nop 0
	global_load_lds_dwordx4 v1, s[28:29]
	s_mov_b32 m0, s62
	s_nop 0
	global_load_lds_dwordx4 v132, s[28:29]
	s_waitcnt vmcnt(8)
	s_waitcnt lgkmcnt(0)
	s_barrier
	s_setprio 1
	s_waitcnt lgkmcnt(7)
	v_mfma_f32_16x16x32_bf16 v[124:127], v[138:141], v[170:173], v[124:127]
	v_mfma_f32_16x16x32_bf16 v[128:131], v[146:149], v[170:173], v[128:131]
	s_waitcnt lgkmcnt(5)
	v_mfma_f32_16x16x32_bf16 v[112:115], v[138:141], v[178:181], v[112:115]
	v_mfma_f32_16x16x32_bf16 v[108:111], v[146:149], v[178:181], v[108:111]
	s_waitcnt lgkmcnt(3)
	v_mfma_f32_16x16x32_bf16 v[96:99], v[138:141], v[186:189], v[96:99]
	v_mfma_f32_16x16x32_bf16 v[92:95], v[146:149], v[186:189], v[92:95]
	s_waitcnt lgkmcnt(1)
	v_mfma_f32_16x16x32_bf16 v[80:83], v[138:141], v[194:197], v[80:83]
	v_mfma_f32_16x16x32_bf16 v[76:79], v[146:149], v[194:197], v[76:79]
	v_mfma_f32_16x16x32_bf16 v[124:127], v[142:145], v[174:177], v[124:127]
	v_mfma_f32_16x16x32_bf16 v[128:131], v[150:153], v[174:177], v[128:131]
	v_mfma_f32_16x16x32_bf16 v[112:115], v[142:145], v[182:185], v[112:115]
	v_mfma_f32_16x16x32_bf16 v[108:111], v[150:153], v[182:185], v[108:111]
	v_mfma_f32_16x16x32_bf16 v[96:99], v[142:145], v[190:193], v[96:99]
	v_mfma_f32_16x16x32_bf16 v[92:95], v[150:153], v[190:193], v[92:95]
	s_waitcnt lgkmcnt(0)
	v_mfma_f32_16x16x32_bf16 v[80:83], v[142:145], v[202:205], v[80:83]
	v_mfma_f32_16x16x32_bf16 v[76:79], v[150:153], v[202:205], v[76:79]
	s_setprio 0
	s_setprio 1
	v_mfma_f32_16x16x32_bf16 v[120:123], v[154:157], v[170:173], v[120:123]
	v_mfma_f32_16x16x32_bf16 v[116:119], v[162:165], v[170:173], v[116:119]
	v_mfma_f32_16x16x32_bf16 v[104:107], v[154:157], v[178:181], v[104:107]
	v_mfma_f32_16x16x32_bf16 v[100:103], v[162:165], v[178:181], v[100:103]
	v_mfma_f32_16x16x32_bf16 v[88:91], v[154:157], v[186:189], v[88:91]
	v_mfma_f32_16x16x32_bf16 v[84:87], v[162:165], v[186:189], v[84:87]
	v_mfma_f32_16x16x32_bf16 v[72:75], v[154:157], v[194:197], v[72:75]
	v_mfma_f32_16x16x32_bf16 v[68:71], v[162:165], v[194:197], v[68:71]
	v_mfma_f32_16x16x32_bf16 v[120:123], v[158:161], v[174:177], v[120:123]
	v_mfma_f32_16x16x32_bf16 v[116:119], v[166:169], v[174:177], v[116:119]
	v_mfma_f32_16x16x32_bf16 v[104:107], v[158:161], v[182:185], v[104:107]
	v_mfma_f32_16x16x32_bf16 v[100:103], v[166:169], v[182:185], v[100:103]
	v_mfma_f32_16x16x32_bf16 v[88:91], v[158:161], v[190:193], v[88:91]
	v_mfma_f32_16x16x32_bf16 v[84:87], v[166:169], v[190:193], v[84:87]
	v_mfma_f32_16x16x32_bf16 v[72:75], v[158:161], v[202:205], v[72:75]
	v_mfma_f32_16x16x32_bf16 v[68:71], v[166:169], v[202:205], v[68:71]
	s_setprio 0
	s_barrier
	ds_read_b128 v[170:173], v137 offset:16384
	ds_read_b128 v[174:177], v137 offset:17408
	ds_read_b128 v[178:181], v137 offset:18432
	ds_read_b128 v[182:185], v137 offset:19456
	ds_read_b128 v[186:189], v137 offset:20480
	ds_read_b128 v[190:193], v137 offset:21504
	ds_read_b128 v[194:197], v137 offset:22528
	ds_read_b128 v[202:205], v137 offset:23552
	s_mov_b32 m0, s23
	s_nop 0
	global_load_lds_dwordx4 v2, s[38:39]
	s_mov_b32 m0, s42
	s_nop 0
	global_load_lds_dwordx4 v133, s[38:39]
	s_add_u32 s72, s38, 0x80000
	s_addc_u32 s73, s39, 0
	s_mov_b32 m0, s43
	s_nop 0
	global_load_lds_dwordx4 v2, s[72:73]
	s_mov_b32 m0, s48
	s_nop 0
	global_load_lds_dwordx4 v133, s[72:73]
	s_mov_b32 m0, s35
	s_nop 0
	global_load_lds_dwordx4 v1, s[40:41]
	s_mov_b32 m0, s49
	s_nop 0
	global_load_lds_dwordx4 v132, s[40:41]
	s_waitcnt vmcnt(8)
	s_waitcnt lgkmcnt(0)
	s_barrier
	s_setprio 1
	s_waitcnt lgkmcnt(7)
	v_mfma_f32_16x16x32_bf16 v[64:67], v[138:141], v[170:173], v[64:67]
	v_mfma_f32_16x16x32_bf16 v[60:63], v[146:149], v[170:173], v[60:63]
	s_waitcnt lgkmcnt(5)
	v_mfma_f32_16x16x32_bf16 v[48:51], v[138:141], v[178:181], v[48:51]
	v_mfma_f32_16x16x32_bf16 v[44:47], v[146:149], v[178:181], v[44:47]
	s_waitcnt lgkmcnt(3)
	v_mfma_f32_16x16x32_bf16 v[32:35], v[138:141], v[186:189], v[32:35]
	v_mfma_f32_16x16x32_bf16 v[28:31], v[146:149], v[186:189], v[28:31]
	s_waitcnt lgkmcnt(1)
	v_mfma_f32_16x16x32_bf16 v[16:19], v[138:141], v[194:197], v[16:19]
	v_mfma_f32_16x16x32_bf16 v[12:15], v[146:149], v[194:197], v[12:15]
	v_mfma_f32_16x16x32_bf16 v[64:67], v[142:145], v[174:177], v[64:67]
	v_mfma_f32_16x16x32_bf16 v[60:63], v[150:153], v[174:177], v[60:63]
	v_mfma_f32_16x16x32_bf16 v[48:51], v[142:145], v[182:185], v[48:51]
	v_mfma_f32_16x16x32_bf16 v[44:47], v[150:153], v[182:185], v[44:47]
	v_mfma_f32_16x16x32_bf16 v[32:35], v[142:145], v[190:193], v[32:35]
	v_mfma_f32_16x16x32_bf16 v[28:31], v[150:153], v[190:193], v[28:31]
	s_waitcnt lgkmcnt(0)
	v_mfma_f32_16x16x32_bf16 v[16:19], v[142:145], v[202:205], v[16:19]
	v_mfma_f32_16x16x32_bf16 v[12:15], v[150:153], v[202:205], v[12:15]
	s_setprio 0
	s_setprio 1
	v_mfma_f32_16x16x32_bf16 v[56:59], v[154:157], v[170:173], v[56:59]
	v_mfma_f32_16x16x32_bf16 v[52:55], v[162:165], v[170:173], v[52:55]
	v_mfma_f32_16x16x32_bf16 v[40:43], v[154:157], v[178:181], v[40:43]
	v_mfma_f32_16x16x32_bf16 v[36:39], v[162:165], v[178:181], v[36:39]
	v_mfma_f32_16x16x32_bf16 v[24:27], v[154:157], v[186:189], v[24:27]
	v_mfma_f32_16x16x32_bf16 v[20:23], v[162:165], v[186:189], v[20:23]
	v_mfma_f32_16x16x32_bf16 v[8:11], v[154:157], v[194:197], v[8:11]
	v_mfma_f32_16x16x32_bf16 v[4:7], v[162:165], v[194:197], v[4:7]
	v_mfma_f32_16x16x32_bf16 v[56:59], v[158:161], v[174:177], v[56:59]
	v_mfma_f32_16x16x32_bf16 v[52:55], v[166:169], v[174:177], v[52:55]
	v_mfma_f32_16x16x32_bf16 v[40:43], v[158:161], v[182:185], v[40:43]
	v_mfma_f32_16x16x32_bf16 v[36:39], v[166:169], v[182:185], v[36:39]
	v_mfma_f32_16x16x32_bf16 v[24:27], v[158:161], v[190:193], v[24:27]
	v_mfma_f32_16x16x32_bf16 v[20:23], v[166:169], v[190:193], v[20:23]
	v_mfma_f32_16x16x32_bf16 v[8:11], v[158:161], v[202:205], v[8:11]
	v_mfma_f32_16x16x32_bf16 v[4:7], v[166:169], v[202:205], v[4:7]
	s_setprio 0
	s_barrier
	v_add_u32_e32 v150, 0x18000, v136
	v_add_u32_e32 v166, 0x1c000, v136
	ds_read_b128 v[138:141], v150
	ds_read_b128 v[142:145], v150 offset:1024
	ds_read_b128 v[146:149], v150 offset:2048
	ds_read_b128 v[150:153], v150 offset:3072
	ds_read_b128 v[154:157], v166
	ds_read_b128 v[158:161], v166 offset:1024
	ds_read_b128 v[162:165], v166 offset:2048
	ds_read_b128 v[166:169], v166 offset:3072
	ds_read_b128 v[170:173], v137 offset:32768
	ds_read_b128 v[174:177], v137 offset:33792
	ds_read_b128 v[178:181], v137 offset:34816
	ds_read_b128 v[182:185], v137 offset:35840
	ds_read_b128 v[186:189], v137 offset:36864
	ds_read_b128 v[190:193], v137 offset:37888
	ds_read_b128 v[194:197], v137 offset:38912
	ds_read_b128 v[202:205], v137 offset:39936
	s_add_u32 s40, s40, 0x200000
	s_addc_u32 s41, s41, 0
	s_mov_b32 m0, s50
	s_nop 0
	global_load_lds_dwordx4 v1, s[40:41]
	s_mov_b32 m0, s51
	s_nop 0
	global_load_lds_dwordx4 v132, s[40:41]
	s_waitcnt vmcnt(8)
	s_waitcnt lgkmcnt(0)
	s_barrier
	s_setprio 1
	s_waitcnt lgkmcnt(7)
	v_mfma_f32_16x16x32_bf16 v[124:127], v[138:141], v[170:173], v[124:127]
	v_mfma_f32_16x16x32_bf16 v[128:131], v[146:149], v[170:173], v[128:131]
	s_waitcnt lgkmcnt(5)
	v_mfma_f32_16x16x32_bf16 v[112:115], v[138:141], v[178:181], v[112:115]
	v_mfma_f32_16x16x32_bf16 v[108:111], v[146:149], v[178:181], v[108:111]
	s_waitcnt lgkmcnt(3)
	v_mfma_f32_16x16x32_bf16 v[96:99], v[138:141], v[186:189], v[96:99]
	v_mfma_f32_16x16x32_bf16 v[92:95], v[146:149], v[186:189], v[92:95]
	s_waitcnt lgkmcnt(1)
	v_mfma_f32_16x16x32_bf16 v[80:83], v[138:141], v[194:197], v[80:83]
	v_mfma_f32_16x16x32_bf16 v[76:79], v[146:149], v[194:197], v[76:79]
	v_mfma_f32_16x16x32_bf16 v[124:127], v[142:145], v[174:177], v[124:127]
	v_mfma_f32_16x16x32_bf16 v[128:131], v[150:153], v[174:177], v[128:131]
	v_mfma_f32_16x16x32_bf16 v[112:115], v[142:145], v[182:185], v[112:115]
	v_mfma_f32_16x16x32_bf16 v[108:111], v[150:153], v[182:185], v[108:111]
	v_mfma_f32_16x16x32_bf16 v[96:99], v[142:145], v[190:193], v[96:99]
	v_mfma_f32_16x16x32_bf16 v[92:95], v[150:153], v[190:193], v[92:95]
	s_waitcnt lgkmcnt(0)
	v_mfma_f32_16x16x32_bf16 v[80:83], v[142:145], v[202:205], v[80:83]
	v_mfma_f32_16x16x32_bf16 v[76:79], v[150:153], v[202:205], v[76:79]
	s_setprio 0
	s_setprio 1
	v_mfma_f32_16x16x32_bf16 v[120:123], v[154:157], v[170:173], v[120:123]
	v_mfma_f32_16x16x32_bf16 v[116:119], v[162:165], v[170:173], v[116:119]
	v_mfma_f32_16x16x32_bf16 v[104:107], v[154:157], v[178:181], v[104:107]
	v_mfma_f32_16x16x32_bf16 v[100:103], v[162:165], v[178:181], v[100:103]
	v_mfma_f32_16x16x32_bf16 v[88:91], v[154:157], v[186:189], v[88:91]
	v_mfma_f32_16x16x32_bf16 v[84:87], v[162:165], v[186:189], v[84:87]
	v_mfma_f32_16x16x32_bf16 v[72:75], v[154:157], v[194:197], v[72:75]
	v_mfma_f32_16x16x32_bf16 v[68:71], v[162:165], v[194:197], v[68:71]
	v_mfma_f32_16x16x32_bf16 v[120:123], v[158:161], v[174:177], v[120:123]
	v_mfma_f32_16x16x32_bf16 v[116:119], v[166:169], v[174:177], v[116:119]
	v_mfma_f32_16x16x32_bf16 v[104:107], v[158:161], v[182:185], v[104:107]
	v_mfma_f32_16x16x32_bf16 v[100:103], v[166:169], v[182:185], v[100:103]
	v_mfma_f32_16x16x32_bf16 v[88:91], v[158:161], v[190:193], v[88:91]
	v_mfma_f32_16x16x32_bf16 v[84:87], v[166:169], v[190:193], v[84:87]
	v_mfma_f32_16x16x32_bf16 v[72:75], v[158:161], v[202:205], v[72:75]
	v_mfma_f32_16x16x32_bf16 v[68:71], v[166:169], v[202:205], v[68:71]
	s_setprio 0
	s_barrier
	ds_read_b128 v[170:173], v137 offset:49152
	ds_read_b128 v[174:177], v137 offset:50176
	ds_read_b128 v[178:181], v137 offset:51200
	ds_read_b128 v[182:185], v137 offset:52224
	ds_read_b128 v[186:189], v137 offset:53248
	ds_read_b128 v[190:193], v137 offset:54272
	ds_read_b128 v[194:197], v137 offset:55296
	ds_read_b128 v[202:205], v137 offset:56320
	s_add_u32 s40, s38, 0x80
	s_addc_u32 s41, s39, 0
	s_mov_b32 m0, s54
	s_nop 0
	global_load_lds_dwordx4 v2, s[40:41]
	s_add_u32 s38, s38, 0x80080
	s_mov_b32 m0, s55
	s_nop 0
	global_load_lds_dwordx4 v133, s[40:41]
	s_addc_u32 s39, s39, 0
	s_mov_b32 m0, s58
	s_nop 0
	global_load_lds_dwordx4 v2, s[38:39]
	s_mov_b32 m0, s59
	s_nop 0
	global_load_lds_dwordx4 v133, s[38:39]
	s_mov_b32 m0, s56
	s_nop 0
	global_load_lds_dwordx4 v1, s[30:31]
	s_mov_b32 m0, s57
	s_nop 0
	global_load_lds_dwordx4 v132, s[30:31]
	s_waitcnt vmcnt(8)
	s_waitcnt lgkmcnt(0)
	s_barrier
	s_setprio 1
	s_waitcnt lgkmcnt(7)
	v_mfma_f32_16x16x32_bf16 v[64:67], v[138:141], v[170:173], v[64:67]
	v_mfma_f32_16x16x32_bf16 v[60:63], v[146:149], v[170:173], v[60:63]
	s_waitcnt lgkmcnt(5)
	v_mfma_f32_16x16x32_bf16 v[48:51], v[138:141], v[178:181], v[48:51]
	v_mfma_f32_16x16x32_bf16 v[44:47], v[146:149], v[178:181], v[44:47]
	s_waitcnt lgkmcnt(3)
	v_mfma_f32_16x16x32_bf16 v[32:35], v[138:141], v[186:189], v[32:35]
	v_mfma_f32_16x16x32_bf16 v[28:31], v[146:149], v[186:189], v[28:31]
	s_waitcnt lgkmcnt(1)
	v_mfma_f32_16x16x32_bf16 v[16:19], v[138:141], v[194:197], v[16:19]
	v_mfma_f32_16x16x32_bf16 v[12:15], v[146:149], v[194:197], v[12:15]
	v_mfma_f32_16x16x32_bf16 v[64:67], v[142:145], v[174:177], v[64:67]
	v_mfma_f32_16x16x32_bf16 v[60:63], v[150:153], v[174:177], v[60:63]
	v_mfma_f32_16x16x32_bf16 v[48:51], v[142:145], v[182:185], v[48:51]
	v_mfma_f32_16x16x32_bf16 v[44:47], v[150:153], v[182:185], v[44:47]
	v_mfma_f32_16x16x32_bf16 v[32:35], v[142:145], v[190:193], v[32:35]
	v_mfma_f32_16x16x32_bf16 v[28:31], v[150:153], v[190:193], v[28:31]
	s_waitcnt lgkmcnt(0)
	v_mfma_f32_16x16x32_bf16 v[16:19], v[142:145], v[202:205], v[16:19]
	v_mfma_f32_16x16x32_bf16 v[12:15], v[150:153], v[202:205], v[12:15]
	s_setprio 0
	s_setprio 1
	v_mfma_f32_16x16x32_bf16 v[56:59], v[154:157], v[170:173], v[56:59]
	v_mfma_f32_16x16x32_bf16 v[52:55], v[162:165], v[170:173], v[52:55]
	v_mfma_f32_16x16x32_bf16 v[40:43], v[154:157], v[178:181], v[40:43]
	v_mfma_f32_16x16x32_bf16 v[36:39], v[162:165], v[178:181], v[36:39]
	v_mfma_f32_16x16x32_bf16 v[24:27], v[154:157], v[186:189], v[24:27]
	v_mfma_f32_16x16x32_bf16 v[20:23], v[162:165], v[186:189], v[20:23]
	v_mfma_f32_16x16x32_bf16 v[8:11], v[154:157], v[194:197], v[8:11]
	v_mfma_f32_16x16x32_bf16 v[4:7], v[162:165], v[194:197], v[4:7]
	v_mfma_f32_16x16x32_bf16 v[56:59], v[158:161], v[174:177], v[56:59]
	v_mfma_f32_16x16x32_bf16 v[52:55], v[166:169], v[174:177], v[52:55]
	v_mfma_f32_16x16x32_bf16 v[40:43], v[158:161], v[182:185], v[40:43]
	v_mfma_f32_16x16x32_bf16 v[36:39], v[166:169], v[182:185], v[36:39]
	v_mfma_f32_16x16x32_bf16 v[24:27], v[158:161], v[190:193], v[24:27]
	v_mfma_f32_16x16x32_bf16 v[20:23], v[166:169], v[190:193], v[20:23]
	v_mfma_f32_16x16x32_bf16 v[8:11], v[158:161], v[202:205], v[8:11]
	v_mfma_f32_16x16x32_bf16 v[4:7], v[166:169], v[202:205], v[4:7]
	s_setprio 0
	s_barrier
	s_add_u32 s67, s67, 0x100
	s_addc_u32 s68, s68, 0
	s_add_u32 s69, s69, 0x100
	s_addc_u32 s70, s70, 0
	s_add_u32 s28, s28, 0x100
	s_addc_u32 s29, s29, 0
	s_cmp_ge_i32 s71, s53
	s_mov_b32 s30, s71
	s_cbranch_scc0 .LBB0_1309
